# v24: group A K DMA pieces split across first two QK MFMA pairs; first P.V fragment group read before the last two QK MFMAs (counted lgkmcnt)
# baseline (speedup 1.0000x reference)
; #define SBAR() __builtin_amdgcn_sched_barrier(0)
; #define PVR(S, DA, DB, vbase) do { S[0] = tr_read<v_rd_off(DA, 0, 0)>(vbase); S[1] = tr_read<v_rd_off(DA, 0, 1)>(vbase); S[2] = tr_read<v_rd_off(DB, 0, 0)>(vbase); S[3] = tr_read<v_rd_off(DB, 0, 1)>(vbase); \
;     S[4] = tr_read<v_rd_off(DA, 1, 0)>(vbase); S[5] = tr_read<v_rd_off(DA, 1, 1)>(vbase); S[6] = tr_read<v_rd_off(DB, 1, 0)>(vbase); S[7] = tr_read<v_rd_off(DB, 1, 1)>(vbase); } while (0)
; #define RAWBAR() do { asm volatile("s_waitcnt lgkmcnt(0)" ::: "memory"); __builtin_amdgcn_s_barrier(); asm volatile("" ::: "memory"); } while (0)
; #define RAWBAR() do { asm volatile("s_waitcnt lgkmcnt(0)" ::: "memory"); __builtin_amdgcn_s_barrier(); asm volatile("" ::: "memory"); } while (0)
; #define RAWBAR() do { asm volatile("s_waitcnt lgkmcnt(0)" ::: "memory"); __builtin_amdgcn_s_barrier(); asm volatile("" ::: "memory"); } while (0)
; #define RAWBAR() do { asm volatile("s_waitcnt lgkmcnt(0)" ::: "memory"); __builtin_amdgcn_s_barrier(); asm volatile("" ::: "memory"); } while (0)
; #define RAWBAR() do { asm volatile("s_waitcnt lgkmcnt(0)" ::: "memory"); __builtin_amdgcn_s_barrier(); asm volatile("" ::: "memory"); } while (0)
; template <int MODE> ...
;     ...
;   for (int j = 0; j < NT; ++j) {
;     const int buf = j & 1;
;     if (j + 1 < NT) { STAGE((j + 1) * KVBLK, buf ^ 1); }
;     const char* Kb = K_lds + buf * 16384;
;     f32x16 pe = {}, po = {};
; #pragma unroll
;     for (int d0 = 0; d0 < 8; d0 += 2) {
;       const bf16x8 k0 = *reinterpret_cast<const bf16x8*>(Kb + KSWZ(krow, (d0 * 16 + hi * 8) * 2));
;       const bf16x8 k1 = *reinterpret_cast<const bf16x8*>(Kb + KSWZ(krow, ((d0 + 1) * 16 + hi * 8) * 2));
;       pe = __builtin_amdgcn_mfma_f32_32x32x16_bf16(k0, qr[d0], pe, 0, 0, 0);
;       po = __builtin_amdgcn_mfma_f32_32x32x16_bf16(k1, qr[d0 + 1], po, 0, 0, 0); }
;     const int vo = vb0 + buf * 32768;
;     s16x4 R0_[8], R1_[8];
;     PVR(R0_, 0, 1, vo);
;     f32x16 p;
; #pragma unroll
;     for (int r = 0; r < 16; ++r) p[r] = __builtin_amdgcn_exp2f(fmaf(pe[r] + po[r], C, negMc));
;     float ps = 0.f;
; #pragma unroll
;     for (int r = 0; r < 16; ++r) ps += p[r];
;     lsum += ps;
;     const bf16x8 own0 = pk8(p, 0), own1 = pk8(p, 8);
;     SBAR();
;     PV_TAIL4(o, vo, vo + 16384, own0, own1);
;     asm volatile("s_waitcnt vmcnt(0)" ::: "memory");
;     RAWBAR();
;   }
.LBB0_1019:
	ds_read_b128 v[226:229], v225 offset:16384
	ds_read_b128 v[230:233], v223 offset:16384
	ds_read_b128 v[234:237], v222 offset:16384
	ds_read_b128 v[238:241], v221 offset:16384
	v_exp_f32_e32 v144, v144
	v_exp_f32_e32 v145, v145
	v_exp_f32_e32 v146, v146
	v_exp_f32_e32 v147, v147
	s_waitcnt lgkmcnt(2)
	v_mfma_f32_32x32x16_bf16 v[128:143], v[226:229], v[188:191], 0
	v_mfma_f32_32x32x16_bf16 v[128:143], v[230:233], v[184:187], v[128:143]
	ds_read_b128 v[226:229], v202 offset:16384
	ds_read_b128 v[230:233], v203 offset:16384
	s_mov_b32 m0, s24
	s_nop 0
	global_load_lds_dwordx4 v220, s[86:87] sc1
	v_exp_f32_e32 v148, v148
	v_exp_f32_e32 v149, v149
	v_exp_f32_e32 v150, v150
	v_exp_f32_e32 v151, v151
	v_add_f32_e32 v246, v144, v145
	v_add_f32_e32 v246, v146, v246
	v_add_f32_e32 v246, v147, v246
	s_waitcnt lgkmcnt(2)
	v_mfma_f32_32x32x16_bf16 v[128:143], v[234:237], v[180:183], v[128:143]
	v_mfma_f32_32x32x16_bf16 v[128:143], v[238:241], v[176:179], v[128:143]
	ds_read_b128 v[234:237], v204 offset:16384
	ds_read_b128 v[238:241], v205 offset:16384
	s_add_i32 m0, s24, 0x2000
	s_nop 0
	global_load_lds_dwordx4 v219, s[86:87] sc1
	v_exp_f32_e32 v152, v152
	v_exp_f32_e32 v153, v153
	v_exp_f32_e32 v154, v154
	v_exp_f32_e32 v155, v155
	v_add_f32_e32 v246, v148, v246
	v_add_f32_e32 v246, v149, v246
	v_add_f32_e32 v246, v150, v246
	v_add_f32_e32 v246, v151, v246
	s_waitcnt lgkmcnt(2)
	v_mfma_f32_32x32x16_bf16 v[128:143], v[226:229], v[172:175], v[128:143]
	v_mfma_f32_32x32x16_bf16 v[128:143], v[230:233], v[168:171], v[128:143]
	v_exp_f32_e32 v156, v156
	v_exp_f32_e32 v157, v157
	v_exp_f32_e32 v158, v158
	v_exp_f32_e32 v159, v159
	v_add_f32_e32 v246, v152, v246
	v_add_f32_e32 v246, v153, v246
	v_add_f32_e32 v246, v154, v246
	v_add_f32_e32 v246, v155, v246
	v_cvt_pk_bf16_f32 v226, v144, v145
	v_cvt_pk_bf16_f32 v227, v146, v147
	v_cvt_pk_bf16_f32 v228, v148, v149
	v_cvt_pk_bf16_f32 v229, v150, v151
	v_add_u32_e32 v245, s84, v214
	ds_read_b64_tr_b16 v[144:145], v245 offset:0
	ds_read_b64_tr_b16 v[146:147], v245 offset:2048
	ds_read_b64_tr_b16 v[148:149], v245 offset:512
	ds_read_b64_tr_b16 v[150:151], v245 offset:2560
	s_waitcnt lgkmcnt(4)
	v_mfma_f32_32x32x16_bf16 v[128:143], v[234:237], v[164:167], v[128:143]
	v_mfma_f32_32x32x16_bf16 v[128:143], v[238:241], v[160:163], v[128:143]
	s_add_i32 s85, s84, 0x8000
	s_cmp_eq_u32 s85, 0x18000
	s_cselect_b32 s85, 0, s85
	ds_read_b64_tr_b16 v[234:235], v245 offset:4096
	ds_read_b64_tr_b16 v[236:237], v245 offset:6144
	ds_read_b64_tr_b16 v[238:239], v245 offset:4608
	ds_read_b64_tr_b16 v[240:241], v245 offset:6656
	v_add_f32_e32 v246, v156, v246
	v_add_f32_e32 v246, v157, v246
	v_add_f32_e32 v246, v158, v246
	v_add_f32_e32 v246, v159, v246
	v_cvt_pk_bf16_f32 v230, v152, v153
	v_cvt_pk_bf16_f32 v231, v154, v155
	v_cvt_pk_bf16_f32 v232, v156, v157
	v_cvt_pk_bf16_f32 v233, v158, v159
	v_add_f32_e32 v215, v215, v246
	ds_read_b64_tr_b16 v[152:153], v245 offset:1024
	ds_read_b64_tr_b16 v[154:155], v245 offset:3072
	ds_read_b64_tr_b16 v[156:157], v245 offset:1536
	ds_read_b64_tr_b16 v[158:159], v245 offset:3584
	s_waitcnt lgkmcnt(8)
	v_mfma_f32_32x32x16_bf16 v[112:127], v[226:229], v[144:147], v[112:127]
	v_mfma_f32_32x32x16_bf16 v[96:111], v[226:229], v[148:151], v[96:111]
	ds_read_b64_tr_b16 v[144:145], v245 offset:5120
	ds_read_b64_tr_b16 v[146:147], v245 offset:7168
	ds_read_b64_tr_b16 v[148:149], v245 offset:5632
	ds_read_b64_tr_b16 v[150:151], v245 offset:7680
	s_add_i32 s41, s85, s24
	s_add_i32 m0, s41, 0x8000
	s_nop 0
	global_load_lds_dwordx4 v218, s[2:3] sc1
	s_waitcnt lgkmcnt(8)
	v_mfma_f32_32x32x16_bf16 v[112:127], v[230:233], v[234:237], v[112:127]
	v_mfma_f32_32x32x16_bf16 v[96:111], v[230:233], v[238:241], v[96:111]
	ds_read_b64_tr_b16 v[234:235], v245 offset:16384
	ds_read_b64_tr_b16 v[236:237], v245 offset:18432
	ds_read_b64_tr_b16 v[238:239], v245 offset:16896
	ds_read_b64_tr_b16 v[240:241], v245 offset:18944
	s_add_i32 s41, s85, s24
	s_add_i32 m0, s41, 0xa000
	s_nop 0
	global_load_lds_dwordx4 v217, s[2:3] sc1
	s_waitcnt lgkmcnt(8)
	v_mfma_f32_32x32x16_bf16 v[80:95], v[226:229], v[152:155], v[80:95]
	v_mfma_f32_32x32x16_bf16 v[64:79], v[226:229], v[156:159], v[64:79]
	ds_read_b64_tr_b16 v[152:153], v245 offset:20480
	ds_read_b64_tr_b16 v[154:155], v245 offset:22528
	ds_read_b64_tr_b16 v[156:157], v245 offset:20992
	ds_read_b64_tr_b16 v[158:159], v245 offset:23040
	s_add_i32 s41, s85, s24
	s_add_i32 m0, s41, 0xc000
	s_nop 0
	global_load_lds_dwordx4 v242, s[2:3] sc1
	s_waitcnt lgkmcnt(8)
	v_mfma_f32_32x32x16_bf16 v[80:95], v[230:233], v[144:147], v[80:95]
	v_mfma_f32_32x32x16_bf16 v[64:79], v[230:233], v[148:151], v[64:79]
	ds_read_b64_tr_b16 v[144:145], v245 offset:17408
	ds_read_b64_tr_b16 v[146:147], v245 offset:19456
	ds_read_b64_tr_b16 v[148:149], v245 offset:17920
	ds_read_b64_tr_b16 v[150:151], v245 offset:19968
	s_add_i32 s41, s85, s24
	s_add_i32 m0, s41, 0xe000
	s_nop 0
	global_load_lds_dwordx4 v243, s[2:3] sc1
	s_waitcnt lgkmcnt(8)
	v_mfma_f32_32x32x16_bf16 v[48:63], v[226:229], v[234:237], v[48:63]
	v_mfma_f32_32x32x16_bf16 v[32:47], v[226:229], v[238:241], v[32:47]
	ds_read_b64_tr_b16 v[234:235], v245 offset:21504
	ds_read_b64_tr_b16 v[236:237], v245 offset:23552
	ds_read_b64_tr_b16 v[238:239], v245 offset:22016
	ds_read_b64_tr_b16 v[240:241], v245 offset:24064
	s_waitcnt lgkmcnt(8)
	v_mfma_f32_32x32x16_bf16 v[48:63], v[230:233], v[152:155], v[48:63]
	v_mfma_f32_32x32x16_bf16 v[32:47], v[230:233], v[156:159], v[32:47]
	s_waitcnt lgkmcnt(0)
	v_mfma_f32_32x32x16_bf16 v[16:31], v[226:229], v[144:147], v[16:31]
	s_waitcnt vmcnt(0)
	s_barrier
; #define SBAR() __builtin_amdgcn_sched_barrier(0)
; #define PVR(S, DA, DB, vbase) do { S[0] = tr_read<v_rd_off(DA, 0, 0)>(vbase); S[1] = tr_read<v_rd_off(DA, 0, 1)>(vbase); S[2] = tr_read<v_rd_off(DB, 0, 0)>(vbase); S[3] = tr_read<v_rd_off(DB, 0, 1)>(vbase); \
;     S[4] = tr_read<v_rd_off(DA, 1, 0)>(vbase); S[5] = tr_read<v_rd_off(DA, 1, 1)>(vbase); S[6] = tr_read<v_rd_off(DB, 1, 0)>(vbase); S[7] = tr_read<v_rd_off(DB, 1, 1)>(vbase); } while (0)
; #define RAWBAR() do { asm volatile("s_waitcnt lgkmcnt(0)" ::: "memory"); __builtin_amdgcn_s_barrier(); asm volatile("" ::: "memory"); } while (0)
; #define RAWBAR() do { asm volatile("s_waitcnt lgkmcnt(0)" ::: "memory"); __builtin_amdgcn_s_barrier(); asm volatile("" ::: "memory"); } while (0)
; #define RAWBAR() do { asm volatile("s_waitcnt lgkmcnt(0)" ::: "memory"); __builtin_amdgcn_s_barrier(); asm volatile("" ::: "memory"); } while (0)
; #define RAWBAR() do { asm volatile("s_waitcnt lgkmcnt(0)" ::: "memory"); __builtin_amdgcn_s_barrier(); asm volatile("" ::: "memory"); } while (0)
; #define RAWBAR() do { asm volatile("s_waitcnt lgkmcnt(0)" ::: "memory"); __builtin_amdgcn_s_barrier(); asm volatile("" ::: "memory"); } while (0)
; template <int MODE> ...
;     ...
;   for (int j = 0; j < NT; ++j) {
;     const int buf = j & 1;
;     if (j + 1 < NT) { STAGE((j + 1) * KVBLK, buf ^ 1); }
;     const char* Kb = K_lds + buf * 16384;
;     f32x16 pe = {}, po = {};
; #pragma unroll
;     for (int d0 = 0; d0 < 8; d0 += 2) {
;       const bf16x8 k0 = *reinterpret_cast<const bf16x8*>(Kb + KSWZ(krow, (d0 * 16 + hi * 8) * 2));
;       const bf16x8 k1 = *reinterpret_cast<const bf16x8*>(Kb + KSWZ(krow, ((d0 + 1) * 16 + hi * 8) * 2));
;       pe = __builtin_amdgcn_mfma_f32_32x32x16_bf16(k0, qr[d0], pe, 0, 0, 0);
;       po = __builtin_amdgcn_mfma_f32_32x32x16_bf16(k1, qr[d0 + 1], po, 0, 0, 0); }
;     const int vo = vb0 + buf * 32768;
;     s16x4 R0_[8], R1_[8];
;     PVR(R0_, 0, 1, vo);
;     f32x16 p;
; #pragma unroll
;     for (int r = 0; r < 16; ++r) p[r] = __builtin_amdgcn_exp2f(fmaf(pe[r] + po[r], C, negMc));
;     float ps = 0.f;
; #pragma unroll
;     for (int r = 0; r < 16; ++r) ps += p[r];
;     lsum += ps;
;     const bf16x8 own0 = pk8(p, 0), own1 = pk8(p, 8);
;     SBAR();
;     PV_TAIL4(o, vo, vo + 16384, own0, own1);
;     asm volatile("s_waitcnt vmcnt(0)" ::: "memory");
;     RAWBAR();
;   }
	s_add_u32 s86, s86, 0x4000
	s_addc_u32 s87, s87, 0
	s_add_u32 s2, s2, 0x8000
	s_addc_u32 s3, s3, 0
	v_mfma_f32_32x32x16_bf16 v[0:15], v[226:229], v[148:151], v[0:15]
	v_mfma_f32_32x32x16_bf16 v[16:31], v[230:233], v[234:237], v[16:31]
	v_mfma_f32_32x32x16_bf16 v[0:15], v[230:233], v[238:241], v[0:15]
	s_add_i32 s84, s84, 0x8000
	s_cmp_eq_u32 s84, 0x18000
	s_cselect_b32 s84, 0, s84
	ds_read_b128 v[226:229], v225 offset:0
	ds_read_b128 v[230:233], v223 offset:0
	ds_read_b128 v[234:237], v222 offset:0
	ds_read_b128 v[238:241], v221 offset:0
	v_exp_f32_e32 v128, v128
	v_exp_f32_e32 v129, v129
	v_exp_f32_e32 v130, v130
	v_exp_f32_e32 v131, v131
	s_waitcnt lgkmcnt(2)
	v_mfma_f32_32x32x16_bf16 v[144:159], v[226:229], v[188:191], 0
	v_mfma_f32_32x32x16_bf16 v[144:159], v[230:233], v[184:187], v[144:159]
	ds_read_b128 v[226:229], v202 offset:0
	ds_read_b128 v[230:233], v203 offset:0
	s_add_i32 m0, s24, 0x4000
	s_nop 0
	global_load_lds_dwordx4 v220, s[86:87] sc1
	v_exp_f32_e32 v132, v132
	v_exp_f32_e32 v133, v133
	v_exp_f32_e32 v134, v134
	v_exp_f32_e32 v135, v135
	v_add_f32_e32 v246, v128, v129
	v_add_f32_e32 v246, v130, v246
	v_add_f32_e32 v246, v131, v246
	s_waitcnt lgkmcnt(2)
	v_mfma_f32_32x32x16_bf16 v[144:159], v[234:237], v[180:183], v[144:159]
	v_mfma_f32_32x32x16_bf16 v[144:159], v[238:241], v[176:179], v[144:159]
	ds_read_b128 v[234:237], v204 offset:0
	ds_read_b128 v[238:241], v205 offset:0
	s_add_i32 m0, s24, 0x6000
	s_nop 0
	global_load_lds_dwordx4 v219, s[86:87] sc1
	v_exp_f32_e32 v136, v136
	v_exp_f32_e32 v137, v137
	v_exp_f32_e32 v138, v138
	v_exp_f32_e32 v139, v139
	v_add_f32_e32 v246, v132, v246
	v_add_f32_e32 v246, v133, v246
	v_add_f32_e32 v246, v134, v246
	v_add_f32_e32 v246, v135, v246
	s_waitcnt lgkmcnt(2)
	v_mfma_f32_32x32x16_bf16 v[144:159], v[226:229], v[172:175], v[144:159]
	v_mfma_f32_32x32x16_bf16 v[144:159], v[230:233], v[168:171], v[144:159]
	v_exp_f32_e32 v140, v140
	v_exp_f32_e32 v141, v141
	v_exp_f32_e32 v142, v142
	v_exp_f32_e32 v143, v143
	v_add_f32_e32 v246, v136, v246
	v_add_f32_e32 v246, v137, v246
	v_add_f32_e32 v246, v138, v246
	v_add_f32_e32 v246, v139, v246
	v_cvt_pk_bf16_f32 v226, v128, v129
	v_cvt_pk_bf16_f32 v227, v130, v131
	v_cvt_pk_bf16_f32 v228, v132, v133
	v_cvt_pk_bf16_f32 v229, v134, v135
	v_add_u32_e32 v245, s84, v214
	ds_read_b64_tr_b16 v[128:129], v245 offset:0
	ds_read_b64_tr_b16 v[130:131], v245 offset:2048
	ds_read_b64_tr_b16 v[132:133], v245 offset:512
	ds_read_b64_tr_b16 v[134:135], v245 offset:2560
	s_waitcnt lgkmcnt(4)
	v_mfma_f32_32x32x16_bf16 v[144:159], v[234:237], v[164:167], v[144:159]
	v_mfma_f32_32x32x16_bf16 v[144:159], v[238:241], v[160:163], v[144:159]
	s_add_i32 s85, s84, 0x8000
	s_cmp_eq_u32 s85, 0x18000
	s_cselect_b32 s85, 0, s85
	ds_read_b64_tr_b16 v[234:235], v245 offset:4096
	ds_read_b64_tr_b16 v[236:237], v245 offset:6144
	ds_read_b64_tr_b16 v[238:239], v245 offset:4608
	ds_read_b64_tr_b16 v[240:241], v245 offset:6656
	v_add_f32_e32 v246, v140, v246
	v_add_f32_e32 v246, v141, v246
	v_add_f32_e32 v246, v142, v246
	v_add_f32_e32 v246, v143, v246
	v_cvt_pk_bf16_f32 v230, v136, v137
	v_cvt_pk_bf16_f32 v231, v138, v139
	v_cvt_pk_bf16_f32 v232, v140, v141
	v_cvt_pk_bf16_f32 v233, v142, v143
	v_add_f32_e32 v215, v215, v246
	ds_read_b64_tr_b16 v[136:137], v245 offset:1024
	ds_read_b64_tr_b16 v[138:139], v245 offset:3072
	ds_read_b64_tr_b16 v[140:141], v245 offset:1536
	ds_read_b64_tr_b16 v[142:143], v245 offset:3584
	s_waitcnt lgkmcnt(8)
	v_mfma_f32_32x32x16_bf16 v[112:127], v[226:229], v[128:131], v[112:127]
	v_mfma_f32_32x32x16_bf16 v[96:111], v[226:229], v[132:135], v[96:111]
	ds_read_b64_tr_b16 v[128:129], v245 offset:5120
	ds_read_b64_tr_b16 v[130:131], v245 offset:7168
	ds_read_b64_tr_b16 v[132:133], v245 offset:5632
	ds_read_b64_tr_b16 v[134:135], v245 offset:7680
	s_add_i32 s41, s85, s24
	s_add_i32 m0, s41, 0x8000
	s_nop 0
	global_load_lds_dwordx4 v218, s[2:3] sc1
	s_waitcnt lgkmcnt(8)
	v_mfma_f32_32x32x16_bf16 v[112:127], v[230:233], v[234:237], v[112:127]
	v_mfma_f32_32x32x16_bf16 v[96:111], v[230:233], v[238:241], v[96:111]
	ds_read_b64_tr_b16 v[234:235], v245 offset:16384
	ds_read_b64_tr_b16 v[236:237], v245 offset:18432
	ds_read_b64_tr_b16 v[238:239], v245 offset:16896
	ds_read_b64_tr_b16 v[240:241], v245 offset:18944
	s_add_i32 s41, s85, s24
	s_add_i32 m0, s41, 0xa000
	s_nop 0
	global_load_lds_dwordx4 v217, s[2:3] sc1
	s_waitcnt lgkmcnt(8)
	v_mfma_f32_32x32x16_bf16 v[80:95], v[226:229], v[136:139], v[80:95]
	v_mfma_f32_32x32x16_bf16 v[64:79], v[226:229], v[140:143], v[64:79]
	ds_read_b64_tr_b16 v[136:137], v245 offset:20480
	ds_read_b64_tr_b16 v[138:139], v245 offset:22528
	ds_read_b64_tr_b16 v[140:141], v245 offset:20992
	ds_read_b64_tr_b16 v[142:143], v245 offset:23040
	s_add_i32 s41, s85, s24
	s_add_i32 m0, s41, 0xc000
	s_nop 0
	global_load_lds_dwordx4 v242, s[2:3] sc1
	s_waitcnt lgkmcnt(8)
	v_mfma_f32_32x32x16_bf16 v[80:95], v[230:233], v[128:131], v[80:95]
	v_mfma_f32_32x32x16_bf16 v[64:79], v[230:233], v[132:135], v[64:79]
	ds_read_b64_tr_b16 v[128:129], v245 offset:17408
	ds_read_b64_tr_b16 v[130:131], v245 offset:19456
	ds_read_b64_tr_b16 v[132:133], v245 offset:17920
	ds_read_b64_tr_b16 v[134:135], v245 offset:19968
	s_add_i32 s41, s85, s24
	s_add_i32 m0, s41, 0xe000
	s_nop 0
	global_load_lds_dwordx4 v243, s[2:3] sc1
	s_waitcnt lgkmcnt(8)
	v_mfma_f32_32x32x16_bf16 v[48:63], v[226:229], v[234:237], v[48:63]
	v_mfma_f32_32x32x16_bf16 v[32:47], v[226:229], v[238:241], v[32:47]
	ds_read_b64_tr_b16 v[234:235], v245 offset:21504
	ds_read_b64_tr_b16 v[236:237], v245 offset:23552
	ds_read_b64_tr_b16 v[238:239], v245 offset:22016
	ds_read_b64_tr_b16 v[240:241], v245 offset:24064
	s_waitcnt lgkmcnt(8)
	v_mfma_f32_32x32x16_bf16 v[48:63], v[230:233], v[136:139], v[48:63]
	v_mfma_f32_32x32x16_bf16 v[32:47], v[230:233], v[140:143], v[32:47]
	s_waitcnt lgkmcnt(0)
	v_mfma_f32_32x32x16_bf16 v[16:31], v[226:229], v[128:131], v[16:31]
	s_waitcnt vmcnt(0)
	s_barrier
	s_add_u32 s86, s86, 0x4000
	s_addc_u32 s87, s87, 0
	s_add_u32 s2, s2, 0x8000
	s_addc_u32 s3, s3, 0
	v_mfma_f32_32x32x16_bf16 v[0:15], v[226:229], v[132:135], v[0:15]
	v_mfma_f32_32x32x16_bf16 v[16:31], v[230:233], v[234:237], v[16:31]
	v_mfma_f32_32x32x16_bf16 v[0:15], v[230:233], v[238:241], v[0:15]
	s_add_i32 s84, s84, 0x8000
	s_cmp_eq_u32 s84, 0x18000
	s_cselect_b32 s84, 0, s84
	s_add_i32 s25, s25, 1
	s_cmpk_eq_i32 s25, 0x82
	s_cbranch_scc0 .LBB0_1019
	s_barrier
	s_branch .Lattn_join_m0

; #define SBAR() __builtin_amdgcn_sched_barrier(0)
; #define PVR(S, DA, DB, vbase) do { S[0] = tr_read<v_rd_off(DA, 0, 0)>(vbase); S[1] = tr_read<v_rd_off(DA, 0, 1)>(vbase); S[2] = tr_read<v_rd_off(DB, 0, 0)>(vbase); S[3] = tr_read<v_rd_off(DB, 0, 1)>(vbase); \
;     S[4] = tr_read<v_rd_off(DA, 1, 0)>(vbase); S[5] = tr_read<v_rd_off(DA, 1, 1)>(vbase); S[6] = tr_read<v_rd_off(DB, 1, 0)>(vbase); S[7] = tr_read<v_rd_off(DB, 1, 1)>(vbase); } while (0)
; #define RAWBAR() do { asm volatile("s_waitcnt lgkmcnt(0)" ::: "memory"); __builtin_amdgcn_s_barrier(); asm volatile("" ::: "memory"); } while (0)
; #define RAWBAR() do { asm volatile("s_waitcnt lgkmcnt(0)" ::: "memory"); __builtin_amdgcn_s_barrier(); asm volatile("" ::: "memory"); } while (0)
; #define RAWBAR() do { asm volatile("s_waitcnt lgkmcnt(0)" ::: "memory"); __builtin_amdgcn_s_barrier(); asm volatile("" ::: "memory"); } while (0)
; #define RAWBAR() do { asm volatile("s_waitcnt lgkmcnt(0)" ::: "memory"); __builtin_amdgcn_s_barrier(); asm volatile("" ::: "memory"); } while (0)
; #define RAWBAR() do { asm volatile("s_waitcnt lgkmcnt(0)" ::: "memory"); __builtin_amdgcn_s_barrier(); asm volatile("" ::: "memory"); } while (0)
; template <int MODE> ...
;     ...
;   for (int j = 0; j < NT; ++j) {
;     const int buf = j & 1;
;     if (j + 1 < NT) { STAGE((j + 1) * KVBLK, buf ^ 1); }
;     const char* Kb = K_lds + buf * 16384;
;     f32x16 pe = {}, po = {};
; #pragma unroll
;     for (int d0 = 0; d0 < 8; d0 += 2) {
;       const bf16x8 k0 = *reinterpret_cast<const bf16x8*>(Kb + KSWZ(krow, (d0 * 16 + hi * 8) * 2));
;       const bf16x8 k1 = *reinterpret_cast<const bf16x8*>(Kb + KSWZ(krow, ((d0 + 1) * 16 + hi * 8) * 2));
;       pe = __builtin_amdgcn_mfma_f32_32x32x16_bf16(k0, qr[d0], pe, 0, 0, 0);
;       po = __builtin_amdgcn_mfma_f32_32x32x16_bf16(k1, qr[d0 + 1], po, 0, 0, 0); }
;     const int vo = vb0 + buf * 32768;
;     s16x4 R0_[8], R1_[8];
;     PVR(R0_, 0, 1, vo);
;     f32x16 p;
; #pragma unroll
;     for (int r = 0; r < 16; ++r) p[r] = __builtin_amdgcn_exp2f(fmaf(pe[r] + po[r], C, negMc));
;     float ps = 0.f;
; #pragma unroll
;     for (int r = 0; r < 16; ++r) ps += p[r];
;     lsum += ps;
;     const bf16x8 own0 = pk8(p, 0), own1 = pk8(p, 8);
;     SBAR();
;     PV_TAIL4(o, vo, vo + 16384, own0, own1);
;     asm volatile("s_waitcnt vmcnt(0)" ::: "memory");
;     RAWBAR();
;   }
.LattnB_m0:
	ds_read_b128 v[226:229], v225 offset:16384
	ds_read_b128 v[230:233], v223 offset:16384
	ds_read_b128 v[234:237], v222 offset:16384
	ds_read_b128 v[238:241], v221 offset:16384
	v_exp_f32_e32 v144, v144
	v_exp_f32_e32 v145, v145
	v_exp_f32_e32 v146, v146
	v_exp_f32_e32 v147, v147
	s_waitcnt lgkmcnt(2)
	v_mfma_f32_32x32x16_bf16 v[128:143], v[226:229], v[188:191], 0
	v_mfma_f32_32x32x16_bf16 v[128:143], v[230:233], v[184:187], v[128:143]
	ds_read_b128 v[226:229], v202 offset:16384
	ds_read_b128 v[230:233], v203 offset:16384
	v_exp_f32_e32 v148, v148
	v_exp_f32_e32 v149, v149
	v_exp_f32_e32 v150, v150
	v_exp_f32_e32 v151, v151
	v_add_f32_e32 v246, v144, v145
	v_add_f32_e32 v246, v146, v246
	v_add_f32_e32 v246, v147, v246
	s_waitcnt lgkmcnt(2)
	v_mfma_f32_32x32x16_bf16 v[128:143], v[234:237], v[180:183], v[128:143]
	v_mfma_f32_32x32x16_bf16 v[128:143], v[238:241], v[176:179], v[128:143]
	ds_read_b128 v[234:237], v204 offset:16384
	ds_read_b128 v[238:241], v205 offset:16384
	v_exp_f32_e32 v152, v152
	v_exp_f32_e32 v153, v153
	v_exp_f32_e32 v154, v154
	v_exp_f32_e32 v155, v155
	v_add_f32_e32 v246, v148, v246
	v_add_f32_e32 v246, v149, v246
	v_add_f32_e32 v246, v150, v246
	v_add_f32_e32 v246, v151, v246
	s_waitcnt lgkmcnt(2)
	v_mfma_f32_32x32x16_bf16 v[128:143], v[226:229], v[172:175], v[128:143]
	v_mfma_f32_32x32x16_bf16 v[128:143], v[230:233], v[168:171], v[128:143]
	v_exp_f32_e32 v156, v156
	v_exp_f32_e32 v157, v157
	v_exp_f32_e32 v158, v158
	v_exp_f32_e32 v159, v159
	v_add_f32_e32 v246, v152, v246
	v_add_f32_e32 v246, v153, v246
	v_add_f32_e32 v246, v154, v246
	v_add_f32_e32 v246, v155, v246
	v_cvt_pk_bf16_f32 v226, v144, v145
	v_cvt_pk_bf16_f32 v227, v146, v147
	v_cvt_pk_bf16_f32 v228, v148, v149
	v_cvt_pk_bf16_f32 v229, v150, v151
	v_add_u32_e32 v245, s84, v214
	ds_read_b64_tr_b16 v[144:145], v245 offset:0
	ds_read_b64_tr_b16 v[146:147], v245 offset:2048
	ds_read_b64_tr_b16 v[148:149], v245 offset:512
	ds_read_b64_tr_b16 v[150:151], v245 offset:2560
	s_waitcnt lgkmcnt(4)
	v_mfma_f32_32x32x16_bf16 v[128:143], v[234:237], v[164:167], v[128:143]
	v_mfma_f32_32x32x16_bf16 v[128:143], v[238:241], v[160:163], v[128:143]
	s_waitcnt vmcnt(0)
	s_barrier
	s_add_u32 s86, s86, 0x4000
	s_addc_u32 s87, s87, 0
	s_add_u32 s2, s2, 0x8000
	s_addc_u32 s3, s3, 0
	s_sub_u32 s85, s84, 0x8000
	s_cmp_eq_u32 s84, 0
	s_cselect_b32 s85, 0x10000, s85
	ds_read_b64_tr_b16 v[234:235], v245 offset:4096
	ds_read_b64_tr_b16 v[236:237], v245 offset:6144
	ds_read_b64_tr_b16 v[238:239], v245 offset:4608
	ds_read_b64_tr_b16 v[240:241], v245 offset:6656
	v_add_f32_e32 v246, v156, v246
	v_add_f32_e32 v246, v157, v246
	v_add_f32_e32 v246, v158, v246
	v_add_f32_e32 v246, v159, v246
	v_cvt_pk_bf16_f32 v230, v152, v153
	v_cvt_pk_bf16_f32 v231, v154, v155
	v_cvt_pk_bf16_f32 v232, v156, v157
	v_cvt_pk_bf16_f32 v233, v158, v159
	v_add_f32_e32 v215, v215, v246
	ds_read_b64_tr_b16 v[152:153], v245 offset:1024
	ds_read_b64_tr_b16 v[154:155], v245 offset:3072
	ds_read_b64_tr_b16 v[156:157], v245 offset:1536
	ds_read_b64_tr_b16 v[158:159], v245 offset:3584
	s_waitcnt lgkmcnt(8)
	v_mfma_f32_32x32x16_bf16 v[112:127], v[226:229], v[144:147], v[112:127]
	v_mfma_f32_32x32x16_bf16 v[96:111], v[226:229], v[148:151], v[96:111]
	ds_read_b64_tr_b16 v[144:145], v245 offset:5120
	ds_read_b64_tr_b16 v[146:147], v245 offset:7168
	ds_read_b64_tr_b16 v[148:149], v245 offset:5632
	ds_read_b64_tr_b16 v[150:151], v245 offset:7680
	s_add_i32 s41, s85, s24
	s_add_i32 m0, s41, 0x8000
	s_nop 0
	global_load_lds_dwordx4 v218, s[2:3] sc1
	s_waitcnt lgkmcnt(8)
	v_mfma_f32_32x32x16_bf16 v[112:127], v[230:233], v[234:237], v[112:127]
	v_mfma_f32_32x32x16_bf16 v[96:111], v[230:233], v[238:241], v[96:111]
	ds_read_b64_tr_b16 v[234:235], v245 offset:16384
	ds_read_b64_tr_b16 v[236:237], v245 offset:18432
	ds_read_b64_tr_b16 v[238:239], v245 offset:16896
	ds_read_b64_tr_b16 v[240:241], v245 offset:18944
	s_add_i32 s41, s85, s24
	s_add_i32 m0, s41, 0xa000
	s_nop 0
	global_load_lds_dwordx4 v217, s[2:3] sc1
	s_waitcnt lgkmcnt(8)
	v_mfma_f32_32x32x16_bf16 v[80:95], v[226:229], v[152:155], v[80:95]
	v_mfma_f32_32x32x16_bf16 v[64:79], v[226:229], v[156:159], v[64:79]
	ds_read_b64_tr_b16 v[152:153], v245 offset:20480
	ds_read_b64_tr_b16 v[154:155], v245 offset:22528
	ds_read_b64_tr_b16 v[156:157], v245 offset:20992
	ds_read_b64_tr_b16 v[158:159], v245 offset:23040
	s_add_i32 s41, s85, s24
	s_add_i32 m0, s41, 0xc000
	s_nop 0
	global_load_lds_dwordx4 v242, s[2:3] sc1
	s_waitcnt lgkmcnt(8)
	v_mfma_f32_32x32x16_bf16 v[80:95], v[230:233], v[144:147], v[80:95]
	v_mfma_f32_32x32x16_bf16 v[64:79], v[230:233], v[148:151], v[64:79]
	ds_read_b64_tr_b16 v[144:145], v245 offset:17408
	ds_read_b64_tr_b16 v[146:147], v245 offset:19456
	ds_read_b64_tr_b16 v[148:149], v245 offset:17920
	ds_read_b64_tr_b16 v[150:151], v245 offset:19968
	s_add_i32 s41, s85, s24
	s_add_i32 m0, s41, 0xe000
	s_nop 0
	global_load_lds_dwordx4 v243, s[2:3] sc1
	s_waitcnt lgkmcnt(8)
	v_mfma_f32_32x32x16_bf16 v[48:63], v[226:229], v[234:237], v[48:63]
	v_mfma_f32_32x32x16_bf16 v[32:47], v[226:229], v[238:241], v[32:47]
	ds_read_b64_tr_b16 v[234:235], v245 offset:21504
	ds_read_b64_tr_b16 v[236:237], v245 offset:23552
	ds_read_b64_tr_b16 v[238:239], v245 offset:22016
	ds_read_b64_tr_b16 v[240:241], v245 offset:24064
	s_add_i32 m0, s24, 0x4000
	s_nop 0
	global_load_lds_dwordx4 v220, s[86:87] sc1
	s_waitcnt lgkmcnt(8)
	v_mfma_f32_32x32x16_bf16 v[48:63], v[230:233], v[152:155], v[48:63]
	v_mfma_f32_32x32x16_bf16 v[32:47], v[230:233], v[156:159], v[32:47]
	s_add_i32 m0, s24, 0x6000
	s_nop 0
	global_load_lds_dwordx4 v219, s[86:87] sc1
	s_waitcnt lgkmcnt(0)
; #define SBAR() __builtin_amdgcn_sched_barrier(0)
; #define PVR(S, DA, DB, vbase) do { S[0] = tr_read<v_rd_off(DA, 0, 0)>(vbase); S[1] = tr_read<v_rd_off(DA, 0, 1)>(vbase); S[2] = tr_read<v_rd_off(DB, 0, 0)>(vbase); S[3] = tr_read<v_rd_off(DB, 0, 1)>(vbase); \
;     S[4] = tr_read<v_rd_off(DA, 1, 0)>(vbase); S[5] = tr_read<v_rd_off(DA, 1, 1)>(vbase); S[6] = tr_read<v_rd_off(DB, 1, 0)>(vbase); S[7] = tr_read<v_rd_off(DB, 1, 1)>(vbase); } while (0)
; #define RAWBAR() do { asm volatile("s_waitcnt lgkmcnt(0)" ::: "memory"); __builtin_amdgcn_s_barrier(); asm volatile("" ::: "memory"); } while (0)
; #define RAWBAR() do { asm volatile("s_waitcnt lgkmcnt(0)" ::: "memory"); __builtin_amdgcn_s_barrier(); asm volatile("" ::: "memory"); } while (0)
; #define RAWBAR() do { asm volatile("s_waitcnt lgkmcnt(0)" ::: "memory"); __builtin_amdgcn_s_barrier(); asm volatile("" ::: "memory"); } while (0)
; #define RAWBAR() do { asm volatile("s_waitcnt lgkmcnt(0)" ::: "memory"); __builtin_amdgcn_s_barrier(); asm volatile("" ::: "memory"); } while (0)
; #define RAWBAR() do { asm volatile("s_waitcnt lgkmcnt(0)" ::: "memory"); __builtin_amdgcn_s_barrier(); asm volatile("" ::: "memory"); } while (0)
; template <int MODE> ...
;     ...
;   for (int j = 0; j < NT; ++j) {
;     const int buf = j & 1;
;     if (j + 1 < NT) { STAGE((j + 1) * KVBLK, buf ^ 1); }
;     const char* Kb = K_lds + buf * 16384;
;     f32x16 pe = {}, po = {};
; #pragma unroll
;     for (int d0 = 0; d0 < 8; d0 += 2) {
;       const bf16x8 k0 = *reinterpret_cast<const bf16x8*>(Kb + KSWZ(krow, (d0 * 16 + hi * 8) * 2));
;       const bf16x8 k1 = *reinterpret_cast<const bf16x8*>(Kb + KSWZ(krow, ((d0 + 1) * 16 + hi * 8) * 2));
;       pe = __builtin_amdgcn_mfma_f32_32x32x16_bf16(k0, qr[d0], pe, 0, 0, 0);
;       po = __builtin_amdgcn_mfma_f32_32x32x16_bf16(k1, qr[d0 + 1], po, 0, 0, 0); }
;     const int vo = vb0 + buf * 32768;
;     s16x4 R0_[8], R1_[8];
;     PVR(R0_, 0, 1, vo);
;     f32x16 p;
; #pragma unroll
;     for (int r = 0; r < 16; ++r) p[r] = __builtin_amdgcn_exp2f(fmaf(pe[r] + po[r], C, negMc));
;     float ps = 0.f;
; #pragma unroll
;     for (int r = 0; r < 16; ++r) ps += p[r];
;     lsum += ps;
;     const bf16x8 own0 = pk8(p, 0), own1 = pk8(p, 8);
;     SBAR();
;     PV_TAIL4(o, vo, vo + 16384, own0, own1);
;     asm volatile("s_waitcnt vmcnt(0)" ::: "memory");
;     RAWBAR();
;   }
	v_mfma_f32_32x32x16_bf16 v[16:31], v[226:229], v[144:147], v[16:31]
	v_mfma_f32_32x32x16_bf16 v[0:15], v[226:229], v[148:151], v[0:15]
	v_mfma_f32_32x32x16_bf16 v[16:31], v[230:233], v[234:237], v[16:31]
	v_mfma_f32_32x32x16_bf16 v[0:15], v[230:233], v[238:241], v[0:15]
	s_add_i32 s84, s84, 0x8000
	s_cmp_eq_u32 s84, 0x18000
	s_cselect_b32 s84, 0, s84
	ds_read_b128 v[226:229], v225 offset:0
	ds_read_b128 v[230:233], v223 offset:0
	ds_read_b128 v[234:237], v222 offset:0
	ds_read_b128 v[238:241], v221 offset:0
	v_exp_f32_e32 v128, v128
	v_exp_f32_e32 v129, v129
	v_exp_f32_e32 v130, v130
	v_exp_f32_e32 v131, v131
	s_waitcnt lgkmcnt(2)
	v_mfma_f32_32x32x16_bf16 v[144:159], v[226:229], v[188:191], 0
	v_mfma_f32_32x32x16_bf16 v[144:159], v[230:233], v[184:187], v[144:159]
	ds_read_b128 v[226:229], v202 offset:0
	ds_read_b128 v[230:233], v203 offset:0
	v_exp_f32_e32 v132, v132
	v_exp_f32_e32 v133, v133
	v_exp_f32_e32 v134, v134
	v_exp_f32_e32 v135, v135
	v_add_f32_e32 v246, v128, v129
	v_add_f32_e32 v246, v130, v246
	v_add_f32_e32 v246, v131, v246
	s_waitcnt lgkmcnt(2)
	v_mfma_f32_32x32x16_bf16 v[144:159], v[234:237], v[180:183], v[144:159]
	v_mfma_f32_32x32x16_bf16 v[144:159], v[238:241], v[176:179], v[144:159]
	ds_read_b128 v[234:237], v204 offset:0
	ds_read_b128 v[238:241], v205 offset:0
	v_exp_f32_e32 v136, v136
	v_exp_f32_e32 v137, v137
	v_exp_f32_e32 v138, v138
	v_exp_f32_e32 v139, v139
	v_add_f32_e32 v246, v132, v246
	v_add_f32_e32 v246, v133, v246
	v_add_f32_e32 v246, v134, v246
	v_add_f32_e32 v246, v135, v246
	s_waitcnt lgkmcnt(2)
	v_mfma_f32_32x32x16_bf16 v[144:159], v[226:229], v[172:175], v[144:159]
	v_mfma_f32_32x32x16_bf16 v[144:159], v[230:233], v[168:171], v[144:159]
	v_exp_f32_e32 v140, v140
	v_exp_f32_e32 v141, v141
	v_exp_f32_e32 v142, v142
	v_exp_f32_e32 v143, v143
	v_add_f32_e32 v246, v136, v246
	v_add_f32_e32 v246, v137, v246
	v_add_f32_e32 v246, v138, v246
	v_add_f32_e32 v246, v139, v246
	v_cvt_pk_bf16_f32 v226, v128, v129
	v_cvt_pk_bf16_f32 v227, v130, v131
	v_cvt_pk_bf16_f32 v228, v132, v133
	v_cvt_pk_bf16_f32 v229, v134, v135
	v_add_u32_e32 v245, s84, v214
	ds_read_b64_tr_b16 v[128:129], v245 offset:0
	ds_read_b64_tr_b16 v[130:131], v245 offset:2048
	ds_read_b64_tr_b16 v[132:133], v245 offset:512
	ds_read_b64_tr_b16 v[134:135], v245 offset:2560
	s_waitcnt lgkmcnt(4)
	v_mfma_f32_32x32x16_bf16 v[144:159], v[234:237], v[164:167], v[144:159]
	v_mfma_f32_32x32x16_bf16 v[144:159], v[238:241], v[160:163], v[144:159]
	s_waitcnt vmcnt(0)
	s_barrier
	s_add_u32 s86, s86, 0x4000
	s_addc_u32 s87, s87, 0
	s_add_u32 s2, s2, 0x8000
	s_addc_u32 s3, s3, 0
	s_sub_u32 s85, s84, 0x8000
	s_cmp_eq_u32 s84, 0
	s_cselect_b32 s85, 0x10000, s85
	ds_read_b64_tr_b16 v[234:235], v245 offset:4096
	ds_read_b64_tr_b16 v[236:237], v245 offset:6144
	ds_read_b64_tr_b16 v[238:239], v245 offset:4608
	ds_read_b64_tr_b16 v[240:241], v245 offset:6656
	v_add_f32_e32 v246, v140, v246
	v_add_f32_e32 v246, v141, v246
	v_add_f32_e32 v246, v142, v246
	v_add_f32_e32 v246, v143, v246
	v_cvt_pk_bf16_f32 v230, v136, v137
	v_cvt_pk_bf16_f32 v231, v138, v139
	v_cvt_pk_bf16_f32 v232, v140, v141
	v_cvt_pk_bf16_f32 v233, v142, v143
	v_add_f32_e32 v215, v215, v246
	ds_read_b64_tr_b16 v[136:137], v245 offset:1024
	ds_read_b64_tr_b16 v[138:139], v245 offset:3072
	ds_read_b64_tr_b16 v[140:141], v245 offset:1536
	ds_read_b64_tr_b16 v[142:143], v245 offset:3584
	s_waitcnt lgkmcnt(8)
	v_mfma_f32_32x32x16_bf16 v[112:127], v[226:229], v[128:131], v[112:127]
	v_mfma_f32_32x32x16_bf16 v[96:111], v[226:229], v[132:135], v[96:111]
	ds_read_b64_tr_b16 v[128:129], v245 offset:5120
	ds_read_b64_tr_b16 v[130:131], v245 offset:7168
	ds_read_b64_tr_b16 v[132:133], v245 offset:5632
	ds_read_b64_tr_b16 v[134:135], v245 offset:7680
	s_add_i32 s41, s85, s24
	s_add_i32 m0, s41, 0x8000
	s_nop 0
	global_load_lds_dwordx4 v218, s[2:3] sc1
	s_waitcnt lgkmcnt(8)
	v_mfma_f32_32x32x16_bf16 v[112:127], v[230:233], v[234:237], v[112:127]
	v_mfma_f32_32x32x16_bf16 v[96:111], v[230:233], v[238:241], v[96:111]
	ds_read_b64_tr_b16 v[234:235], v245 offset:16384
	ds_read_b64_tr_b16 v[236:237], v245 offset:18432
	ds_read_b64_tr_b16 v[238:239], v245 offset:16896
	ds_read_b64_tr_b16 v[240:241], v245 offset:18944
	s_add_i32 s41, s85, s24
	s_add_i32 m0, s41, 0xa000
	s_nop 0
	global_load_lds_dwordx4 v217, s[2:3] sc1
	s_waitcnt lgkmcnt(8)
	v_mfma_f32_32x32x16_bf16 v[80:95], v[226:229], v[136:139], v[80:95]
	v_mfma_f32_32x32x16_bf16 v[64:79], v[226:229], v[140:143], v[64:79]
	ds_read_b64_tr_b16 v[136:137], v245 offset:20480
	ds_read_b64_tr_b16 v[138:139], v245 offset:22528
	ds_read_b64_tr_b16 v[140:141], v245 offset:20992
	ds_read_b64_tr_b16 v[142:143], v245 offset:23040
	s_add_i32 s41, s85, s24
	s_add_i32 m0, s41, 0xc000
	s_nop 0
	global_load_lds_dwordx4 v242, s[2:3] sc1
	s_waitcnt lgkmcnt(8)
	v_mfma_f32_32x32x16_bf16 v[80:95], v[230:233], v[128:131], v[80:95]
	v_mfma_f32_32x32x16_bf16 v[64:79], v[230:233], v[132:135], v[64:79]
	ds_read_b64_tr_b16 v[128:129], v245 offset:17408
	ds_read_b64_tr_b16 v[130:131], v245 offset:19456
	ds_read_b64_tr_b16 v[132:133], v245 offset:17920
	ds_read_b64_tr_b16 v[134:135], v245 offset:19968
	s_add_i32 s41, s85, s24
	s_add_i32 m0, s41, 0xe000
	s_nop 0
	global_load_lds_dwordx4 v243, s[2:3] sc1
	s_waitcnt lgkmcnt(8)
	v_mfma_f32_32x32x16_bf16 v[48:63], v[226:229], v[234:237], v[48:63]
	v_mfma_f32_32x32x16_bf16 v[32:47], v[226:229], v[238:241], v[32:47]
	ds_read_b64_tr_b16 v[234:235], v245 offset:21504
	ds_read_b64_tr_b16 v[236:237], v245 offset:23552
	ds_read_b64_tr_b16 v[238:239], v245 offset:22016
	ds_read_b64_tr_b16 v[240:241], v245 offset:24064
	s_mov_b32 m0, s24
	s_nop 0
	global_load_lds_dwordx4 v220, s[86:87] sc1
	s_waitcnt lgkmcnt(8)
	v_mfma_f32_32x32x16_bf16 v[48:63], v[230:233], v[136:139], v[48:63]
	v_mfma_f32_32x32x16_bf16 v[32:47], v[230:233], v[140:143], v[32:47]
	s_add_i32 m0, s24, 0x2000
	s_nop 0
	global_load_lds_dwordx4 v219, s[86:87] sc1
	s_waitcnt lgkmcnt(0)
	v_mfma_f32_32x32x16_bf16 v[16:31], v[226:229], v[128:131], v[16:31]
	v_mfma_f32_32x32x16_bf16 v[0:15], v[226:229], v[132:135], v[0:15]
	v_mfma_f32_32x32x16_bf16 v[16:31], v[230:233], v[234:237], v[16:31]
	v_mfma_f32_32x32x16_bf16 v[0:15], v[230:233], v[238:241], v[0:15]
	s_add_i32 s84, s84, 0x8000
	s_cmp_eq_u32 s84, 0x18000
	s_cselect_b32 s84, 0, s84
	s_add_i32 s25, s25, 1
	s_cmpk_eq_i32 s25, 0x82
	s_cbranch_scc0 .LattnB_m0
	s_waitcnt vmcnt(0)
	s_barrier

; #define SBAR() __builtin_amdgcn_sched_barrier(0)
; #define PVR(S, DA, DB, vbase) do { S[0] = tr_read<v_rd_off(DA, 0, 0)>(vbase); S[1] = tr_read<v_rd_off(DA, 0, 1)>(vbase); S[2] = tr_read<v_rd_off(DB, 0, 0)>(vbase); S[3] = tr_read<v_rd_off(DB, 0, 1)>(vbase); \
;     S[4] = tr_read<v_rd_off(DA, 1, 0)>(vbase); S[5] = tr_read<v_rd_off(DA, 1, 1)>(vbase); S[6] = tr_read<v_rd_off(DB, 1, 0)>(vbase); S[7] = tr_read<v_rd_off(DB, 1, 1)>(vbase); } while (0)
; #define RAWBAR() do { asm volatile("s_waitcnt lgkmcnt(0)" ::: "memory"); __builtin_amdgcn_s_barrier(); asm volatile("" ::: "memory"); } while (0)
; #define RAWBAR() do { asm volatile("s_waitcnt lgkmcnt(0)" ::: "memory"); __builtin_amdgcn_s_barrier(); asm volatile("" ::: "memory"); } while (0)
; #define RAWBAR() do { asm volatile("s_waitcnt lgkmcnt(0)" ::: "memory"); __builtin_amdgcn_s_barrier(); asm volatile("" ::: "memory"); } while (0)
; #define RAWBAR() do { asm volatile("s_waitcnt lgkmcnt(0)" ::: "memory"); __builtin_amdgcn_s_barrier(); asm volatile("" ::: "memory"); } while (0)
; #define RAWBAR() do { asm volatile("s_waitcnt lgkmcnt(0)" ::: "memory"); __builtin_amdgcn_s_barrier(); asm volatile("" ::: "memory"); } while (0)
; template <int MODE> ...
;     ...
;   for (int j = 0; j < NT; ++j) {
;     const int buf = j & 1;
;     if (j + 1 < NT) { STAGE((j + 1) * KVBLK, buf ^ 1); }
;     const char* Kb = K_lds + buf * 16384;
;     f32x16 pe = {}, po = {};
; #pragma unroll
;     for (int d0 = 0; d0 < 8; d0 += 2) {
;       const bf16x8 k0 = *reinterpret_cast<const bf16x8*>(Kb + KSWZ(krow, (d0 * 16 + hi * 8) * 2));
;       const bf16x8 k1 = *reinterpret_cast<const bf16x8*>(Kb + KSWZ(krow, ((d0 + 1) * 16 + hi * 8) * 2));
;       pe = __builtin_amdgcn_mfma_f32_32x32x16_bf16(k0, qr[d0], pe, 0, 0, 0);
;       po = __builtin_amdgcn_mfma_f32_32x32x16_bf16(k1, qr[d0 + 1], po, 0, 0, 0); }
;     const int vo = vb0 + buf * 32768;
;     s16x4 R0_[8], R1_[8];
;     PVR(R0_, 0, 1, vo);
;     f32x16 p;
; #pragma unroll
;     for (int r = 0; r < 16; ++r) p[r] = __builtin_amdgcn_exp2f(fmaf(pe[r] + po[r], C, negMc));
;     float ps = 0.f;
; #pragma unroll
;     for (int r = 0; r < 16; ++r) ps += p[r];
;     lsum += ps;
;     const bf16x8 own0 = pk8(p, 0), own1 = pk8(p, 8);
;     SBAR();
;     PV_TAIL4(o, vo, vo + 16384, own0, own1);
;     asm volatile("s_waitcnt vmcnt(0)" ::: "memory");
;     RAWBAR();
;   }
.LBB0_1023:
	ds_read_b128 v[230:233], v229 offset:16384
	ds_read_b128 v[234:237], v228 offset:16384
	ds_read_b128 v[238:241], v227 offset:16384
	ds_read_b128 v[242:245], v226 offset:16384
	v_exp_f32_e32 v144, v144
	v_exp_f32_e32 v145, v145
	v_exp_f32_e32 v146, v146
	v_exp_f32_e32 v147, v147
	s_waitcnt lgkmcnt(2)
	v_mfma_f32_32x32x16_bf16 v[128:143], v[230:233], v[188:191], 0
	v_mfma_f32_32x32x16_bf16 v[128:143], v[234:237], v[184:187], v[128:143]
	ds_read_b128 v[230:233], v204 offset:16384
	ds_read_b128 v[234:237], v205 offset:16384
	s_mov_b32 m0, s34
	s_nop 0
	global_load_lds_dwordx4 v225, s[86:87] sc1
	v_exp_f32_e32 v148, v148
	v_exp_f32_e32 v149, v149
	v_exp_f32_e32 v150, v150
	v_exp_f32_e32 v151, v151
	v_add_f32_e32 v250, v144, v145
	v_add_f32_e32 v250, v146, v250
	v_add_f32_e32 v250, v147, v250
	s_waitcnt lgkmcnt(2)
	v_mfma_f32_32x32x16_bf16 v[128:143], v[238:241], v[180:183], v[128:143]
	v_mfma_f32_32x32x16_bf16 v[128:143], v[242:245], v[176:179], v[128:143]
	ds_read_b128 v[238:241], v206 offset:16384
	ds_read_b128 v[242:245], v207 offset:16384
	s_add_i32 m0, s34, 0x2000
	s_nop 0
	global_load_lds_dwordx4 v223, s[86:87] sc1
	v_exp_f32_e32 v152, v152
	v_exp_f32_e32 v153, v153
	v_exp_f32_e32 v154, v154
	v_exp_f32_e32 v155, v155
	v_add_f32_e32 v250, v148, v250
	v_add_f32_e32 v250, v149, v250
	v_add_f32_e32 v250, v150, v250
	v_add_f32_e32 v250, v151, v250
	s_waitcnt lgkmcnt(2)
	v_mfma_f32_32x32x16_bf16 v[128:143], v[230:233], v[172:175], v[128:143]
	v_mfma_f32_32x32x16_bf16 v[128:143], v[234:237], v[168:171], v[128:143]
	v_exp_f32_e32 v156, v156
	v_exp_f32_e32 v157, v157
	v_exp_f32_e32 v158, v158
	v_exp_f32_e32 v159, v159
	v_add_f32_e32 v250, v152, v250
	v_add_f32_e32 v250, v153, v250
	v_add_f32_e32 v250, v154, v250
	v_add_f32_e32 v250, v155, v250
	v_cvt_pk_bf16_f32 v230, v144, v145
	v_cvt_pk_bf16_f32 v231, v146, v147
	v_cvt_pk_bf16_f32 v232, v148, v149
	v_cvt_pk_bf16_f32 v233, v150, v151
	v_add_u32_e32 v249, s84, v218
	ds_read_b64_tr_b16 v[144:145], v249 offset:0
	ds_read_b64_tr_b16 v[146:147], v249 offset:2048
	ds_read_b64_tr_b16 v[148:149], v249 offset:512
	ds_read_b64_tr_b16 v[150:151], v249 offset:2560
	s_waitcnt lgkmcnt(4)
	v_mfma_f32_32x32x16_bf16 v[128:143], v[238:241], v[164:167], v[128:143]
	v_mfma_f32_32x32x16_bf16 v[128:143], v[242:245], v[160:163], v[128:143]
	s_add_i32 s85, s84, 0x8000
	s_cmp_eq_u32 s85, 0x18000
	s_cselect_b32 s85, 0, s85
	ds_read_b64_tr_b16 v[238:239], v249 offset:4096
	ds_read_b64_tr_b16 v[240:241], v249 offset:6144
	ds_read_b64_tr_b16 v[242:243], v249 offset:4608
	ds_read_b64_tr_b16 v[244:245], v249 offset:6656
	v_add_f32_e32 v250, v156, v250
	v_add_f32_e32 v250, v157, v250
	v_add_f32_e32 v250, v158, v250
	v_add_f32_e32 v250, v159, v250
	v_cvt_pk_bf16_f32 v234, v152, v153
	v_cvt_pk_bf16_f32 v235, v154, v155
	v_cvt_pk_bf16_f32 v236, v156, v157
	v_cvt_pk_bf16_f32 v237, v158, v159
	v_add_f32_e32 v219, v219, v250
	ds_read_b64_tr_b16 v[152:153], v249 offset:1024
	ds_read_b64_tr_b16 v[154:155], v249 offset:3072
	ds_read_b64_tr_b16 v[156:157], v249 offset:1536
	ds_read_b64_tr_b16 v[158:159], v249 offset:3584
	s_waitcnt lgkmcnt(8)
	v_mfma_f32_32x32x16_bf16 v[112:127], v[230:233], v[144:147], v[112:127]
	v_mfma_f32_32x32x16_bf16 v[96:111], v[230:233], v[148:151], v[96:111]
	ds_read_b64_tr_b16 v[144:145], v249 offset:5120
	ds_read_b64_tr_b16 v[146:147], v249 offset:7168
	ds_read_b64_tr_b16 v[148:149], v249 offset:5632
	ds_read_b64_tr_b16 v[150:151], v249 offset:7680
	s_add_i32 s30, s85, s34
	s_add_i32 m0, s30, 0x8000
	s_nop 0
	global_load_lds_dwordx4 v222, s[2:3] sc1
	s_waitcnt lgkmcnt(8)
	v_mfma_f32_32x32x16_bf16 v[112:127], v[234:237], v[238:241], v[112:127]
	v_mfma_f32_32x32x16_bf16 v[96:111], v[234:237], v[242:245], v[96:111]
	ds_read_b64_tr_b16 v[238:239], v249 offset:16384
	ds_read_b64_tr_b16 v[240:241], v249 offset:18432
	ds_read_b64_tr_b16 v[242:243], v249 offset:16896
	ds_read_b64_tr_b16 v[244:245], v249 offset:18944
	s_add_i32 s30, s85, s34
	s_add_i32 m0, s30, 0xa000
	s_nop 0
	global_load_lds_dwordx4 v221, s[2:3] sc1
	s_waitcnt lgkmcnt(8)
	v_mfma_f32_32x32x16_bf16 v[80:95], v[230:233], v[152:155], v[80:95]
	v_mfma_f32_32x32x16_bf16 v[64:79], v[230:233], v[156:159], v[64:79]
	ds_read_b64_tr_b16 v[152:153], v249 offset:20480
	ds_read_b64_tr_b16 v[154:155], v249 offset:22528
	ds_read_b64_tr_b16 v[156:157], v249 offset:20992
	ds_read_b64_tr_b16 v[158:159], v249 offset:23040
	s_add_i32 s30, s85, s34
	s_add_i32 m0, s30, 0xc000
	s_nop 0
	global_load_lds_dwordx4 v246, s[2:3] sc1
	s_waitcnt lgkmcnt(8)
	v_mfma_f32_32x32x16_bf16 v[80:95], v[234:237], v[144:147], v[80:95]
	v_mfma_f32_32x32x16_bf16 v[64:79], v[234:237], v[148:151], v[64:79]
	ds_read_b64_tr_b16 v[144:145], v249 offset:17408
	ds_read_b64_tr_b16 v[146:147], v249 offset:19456
	ds_read_b64_tr_b16 v[148:149], v249 offset:17920
	ds_read_b64_tr_b16 v[150:151], v249 offset:19968
	s_add_i32 s30, s85, s34
	s_add_i32 m0, s30, 0xe000
	s_nop 0
	global_load_lds_dwordx4 v247, s[2:3] sc1
	s_waitcnt lgkmcnt(8)
	v_mfma_f32_32x32x16_bf16 v[32:47], v[230:233], v[238:241], v[32:47]
	v_mfma_f32_32x32x16_bf16 v[16:31], v[230:233], v[242:245], v[16:31]
	ds_read_b64_tr_b16 v[238:239], v249 offset:21504
	ds_read_b64_tr_b16 v[240:241], v249 offset:23552
	ds_read_b64_tr_b16 v[242:243], v249 offset:22016
	ds_read_b64_tr_b16 v[244:245], v249 offset:24064
	s_waitcnt lgkmcnt(8)
	v_mfma_f32_32x32x16_bf16 v[32:47], v[234:237], v[152:155], v[32:47]
	v_mfma_f32_32x32x16_bf16 v[16:31], v[234:237], v[156:159], v[16:31]
	s_waitcnt lgkmcnt(0)
	v_mfma_f32_32x32x16_bf16 v[48:63], v[230:233], v[144:147], v[48:63]
	s_waitcnt vmcnt(0)
	s_barrier
; #define SBAR() __builtin_amdgcn_sched_barrier(0)
; #define PVR(S, DA, DB, vbase) do { S[0] = tr_read<v_rd_off(DA, 0, 0)>(vbase); S[1] = tr_read<v_rd_off(DA, 0, 1)>(vbase); S[2] = tr_read<v_rd_off(DB, 0, 0)>(vbase); S[3] = tr_read<v_rd_off(DB, 0, 1)>(vbase); \
;     S[4] = tr_read<v_rd_off(DA, 1, 0)>(vbase); S[5] = tr_read<v_rd_off(DA, 1, 1)>(vbase); S[6] = tr_read<v_rd_off(DB, 1, 0)>(vbase); S[7] = tr_read<v_rd_off(DB, 1, 1)>(vbase); } while (0)
; #define RAWBAR() do { asm volatile("s_waitcnt lgkmcnt(0)" ::: "memory"); __builtin_amdgcn_s_barrier(); asm volatile("" ::: "memory"); } while (0)
; #define RAWBAR() do { asm volatile("s_waitcnt lgkmcnt(0)" ::: "memory"); __builtin_amdgcn_s_barrier(); asm volatile("" ::: "memory"); } while (0)
; #define RAWBAR() do { asm volatile("s_waitcnt lgkmcnt(0)" ::: "memory"); __builtin_amdgcn_s_barrier(); asm volatile("" ::: "memory"); } while (0)
; #define RAWBAR() do { asm volatile("s_waitcnt lgkmcnt(0)" ::: "memory"); __builtin_amdgcn_s_barrier(); asm volatile("" ::: "memory"); } while (0)
; #define RAWBAR() do { asm volatile("s_waitcnt lgkmcnt(0)" ::: "memory"); __builtin_amdgcn_s_barrier(); asm volatile("" ::: "memory"); } while (0)
; template <int MODE> ...
;     ...
;   for (int j = 0; j < NT; ++j) {
;     const int buf = j & 1;
;     if (j + 1 < NT) { STAGE((j + 1) * KVBLK, buf ^ 1); }
;     const char* Kb = K_lds + buf * 16384;
;     f32x16 pe = {}, po = {};
; #pragma unroll
;     for (int d0 = 0; d0 < 8; d0 += 2) {
;       const bf16x8 k0 = *reinterpret_cast<const bf16x8*>(Kb + KSWZ(krow, (d0 * 16 + hi * 8) * 2));
;       const bf16x8 k1 = *reinterpret_cast<const bf16x8*>(Kb + KSWZ(krow, ((d0 + 1) * 16 + hi * 8) * 2));
;       pe = __builtin_amdgcn_mfma_f32_32x32x16_bf16(k0, qr[d0], pe, 0, 0, 0);
;       po = __builtin_amdgcn_mfma_f32_32x32x16_bf16(k1, qr[d0 + 1], po, 0, 0, 0); }
;     const int vo = vb0 + buf * 32768;
;     s16x4 R0_[8], R1_[8];
;     PVR(R0_, 0, 1, vo);
;     f32x16 p;
; #pragma unroll
;     for (int r = 0; r < 16; ++r) p[r] = __builtin_amdgcn_exp2f(fmaf(pe[r] + po[r], C, negMc));
;     float ps = 0.f;
; #pragma unroll
;     for (int r = 0; r < 16; ++r) ps += p[r];
;     lsum += ps;
;     const bf16x8 own0 = pk8(p, 0), own1 = pk8(p, 8);
;     SBAR();
;     PV_TAIL4(o, vo, vo + 16384, own0, own1);
;     asm volatile("s_waitcnt vmcnt(0)" ::: "memory");
;     RAWBAR();
;   }
	s_add_u32 s86, s86, 0x4000
	s_addc_u32 s87, s87, 0
	s_add_u32 s2, s2, 0x8000
	s_addc_u32 s3, s3, 0
	v_mfma_f32_32x32x16_bf16 v[0:15], v[230:233], v[148:151], v[0:15]
	v_mfma_f32_32x32x16_bf16 v[48:63], v[234:237], v[238:241], v[48:63]
	v_mfma_f32_32x32x16_bf16 v[0:15], v[234:237], v[242:245], v[0:15]
	s_add_i32 s84, s84, 0x8000
	s_cmp_eq_u32 s84, 0x18000
	s_cselect_b32 s84, 0, s84
	ds_read_b128 v[230:233], v229 offset:0
	ds_read_b128 v[234:237], v228 offset:0
	ds_read_b128 v[238:241], v227 offset:0
	ds_read_b128 v[242:245], v226 offset:0
	v_exp_f32_e32 v128, v128
	v_exp_f32_e32 v129, v129
	v_exp_f32_e32 v130, v130
	v_exp_f32_e32 v131, v131
	s_waitcnt lgkmcnt(2)
	v_mfma_f32_32x32x16_bf16 v[144:159], v[230:233], v[188:191], 0
	v_mfma_f32_32x32x16_bf16 v[144:159], v[234:237], v[184:187], v[144:159]
	ds_read_b128 v[230:233], v204 offset:0
	ds_read_b128 v[234:237], v205 offset:0
	s_add_i32 m0, s34, 0x4000
	s_nop 0
	global_load_lds_dwordx4 v225, s[86:87] sc1
	v_exp_f32_e32 v132, v132
	v_exp_f32_e32 v133, v133
	v_exp_f32_e32 v134, v134
	v_exp_f32_e32 v135, v135
	v_add_f32_e32 v250, v128, v129
	v_add_f32_e32 v250, v130, v250
	v_add_f32_e32 v250, v131, v250
	s_waitcnt lgkmcnt(2)
	v_mfma_f32_32x32x16_bf16 v[144:159], v[238:241], v[180:183], v[144:159]
	v_mfma_f32_32x32x16_bf16 v[144:159], v[242:245], v[176:179], v[144:159]
	ds_read_b128 v[238:241], v206 offset:0
	ds_read_b128 v[242:245], v207 offset:0
	s_add_i32 m0, s34, 0x6000
	s_nop 0
	global_load_lds_dwordx4 v223, s[86:87] sc1
	v_exp_f32_e32 v136, v136
	v_exp_f32_e32 v137, v137
	v_exp_f32_e32 v138, v138
	v_exp_f32_e32 v139, v139
	v_add_f32_e32 v250, v132, v250
	v_add_f32_e32 v250, v133, v250
	v_add_f32_e32 v250, v134, v250
	v_add_f32_e32 v250, v135, v250
	s_waitcnt lgkmcnt(2)
	v_mfma_f32_32x32x16_bf16 v[144:159], v[230:233], v[172:175], v[144:159]
	v_mfma_f32_32x32x16_bf16 v[144:159], v[234:237], v[168:171], v[144:159]
	v_exp_f32_e32 v140, v140
	v_exp_f32_e32 v141, v141
	v_exp_f32_e32 v142, v142
	v_exp_f32_e32 v143, v143
	v_add_f32_e32 v250, v136, v250
	v_add_f32_e32 v250, v137, v250
	v_add_f32_e32 v250, v138, v250
	v_add_f32_e32 v250, v139, v250
	v_cvt_pk_bf16_f32 v230, v128, v129
	v_cvt_pk_bf16_f32 v231, v130, v131
	v_cvt_pk_bf16_f32 v232, v132, v133
	v_cvt_pk_bf16_f32 v233, v134, v135
	v_add_u32_e32 v249, s84, v218
	ds_read_b64_tr_b16 v[128:129], v249 offset:0
	ds_read_b64_tr_b16 v[130:131], v249 offset:2048
	ds_read_b64_tr_b16 v[132:133], v249 offset:512
	ds_read_b64_tr_b16 v[134:135], v249 offset:2560
	s_waitcnt lgkmcnt(4)
	v_mfma_f32_32x32x16_bf16 v[144:159], v[238:241], v[164:167], v[144:159]
	v_mfma_f32_32x32x16_bf16 v[144:159], v[242:245], v[160:163], v[144:159]
	s_add_i32 s85, s84, 0x8000
	s_cmp_eq_u32 s85, 0x18000
	s_cselect_b32 s85, 0, s85
	ds_read_b64_tr_b16 v[238:239], v249 offset:4096
	ds_read_b64_tr_b16 v[240:241], v249 offset:6144
	ds_read_b64_tr_b16 v[242:243], v249 offset:4608
	ds_read_b64_tr_b16 v[244:245], v249 offset:6656
	v_add_f32_e32 v250, v140, v250
	v_add_f32_e32 v250, v141, v250
	v_add_f32_e32 v250, v142, v250
	v_add_f32_e32 v250, v143, v250
	v_cvt_pk_bf16_f32 v234, v136, v137
	v_cvt_pk_bf16_f32 v235, v138, v139
	v_cvt_pk_bf16_f32 v236, v140, v141
	v_cvt_pk_bf16_f32 v237, v142, v143
	v_add_f32_e32 v219, v219, v250
	ds_read_b64_tr_b16 v[136:137], v249 offset:1024
	ds_read_b64_tr_b16 v[138:139], v249 offset:3072
	ds_read_b64_tr_b16 v[140:141], v249 offset:1536
	ds_read_b64_tr_b16 v[142:143], v249 offset:3584
	s_waitcnt lgkmcnt(8)
	v_mfma_f32_32x32x16_bf16 v[112:127], v[230:233], v[128:131], v[112:127]
	v_mfma_f32_32x32x16_bf16 v[96:111], v[230:233], v[132:135], v[96:111]
	ds_read_b64_tr_b16 v[128:129], v249 offset:5120
	ds_read_b64_tr_b16 v[130:131], v249 offset:7168
	ds_read_b64_tr_b16 v[132:133], v249 offset:5632
	ds_read_b64_tr_b16 v[134:135], v249 offset:7680
	s_add_i32 s30, s85, s34
	s_add_i32 m0, s30, 0x8000
	s_nop 0
	global_load_lds_dwordx4 v222, s[2:3] sc1
	s_waitcnt lgkmcnt(8)
	v_mfma_f32_32x32x16_bf16 v[112:127], v[234:237], v[238:241], v[112:127]
	v_mfma_f32_32x32x16_bf16 v[96:111], v[234:237], v[242:245], v[96:111]
	ds_read_b64_tr_b16 v[238:239], v249 offset:16384
	ds_read_b64_tr_b16 v[240:241], v249 offset:18432
	ds_read_b64_tr_b16 v[242:243], v249 offset:16896
	ds_read_b64_tr_b16 v[244:245], v249 offset:18944
	s_add_i32 s30, s85, s34
	s_add_i32 m0, s30, 0xa000
	s_nop 0
	global_load_lds_dwordx4 v221, s[2:3] sc1
	s_waitcnt lgkmcnt(8)
	v_mfma_f32_32x32x16_bf16 v[80:95], v[230:233], v[136:139], v[80:95]
	v_mfma_f32_32x32x16_bf16 v[64:79], v[230:233], v[140:143], v[64:79]
	ds_read_b64_tr_b16 v[136:137], v249 offset:20480
	ds_read_b64_tr_b16 v[138:139], v249 offset:22528
	ds_read_b64_tr_b16 v[140:141], v249 offset:20992
	ds_read_b64_tr_b16 v[142:143], v249 offset:23040
	s_add_i32 s30, s85, s34
	s_add_i32 m0, s30, 0xc000
	s_nop 0
	global_load_lds_dwordx4 v246, s[2:3] sc1
	s_waitcnt lgkmcnt(8)
	v_mfma_f32_32x32x16_bf16 v[80:95], v[234:237], v[128:131], v[80:95]
	v_mfma_f32_32x32x16_bf16 v[64:79], v[234:237], v[132:135], v[64:79]
	ds_read_b64_tr_b16 v[128:129], v249 offset:17408
	ds_read_b64_tr_b16 v[130:131], v249 offset:19456
	ds_read_b64_tr_b16 v[132:133], v249 offset:17920
	ds_read_b64_tr_b16 v[134:135], v249 offset:19968
	s_add_i32 s30, s85, s34
	s_add_i32 m0, s30, 0xe000
	s_nop 0
	global_load_lds_dwordx4 v247, s[2:3] sc1
	s_waitcnt lgkmcnt(8)
	v_mfma_f32_32x32x16_bf16 v[32:47], v[230:233], v[238:241], v[32:47]
	v_mfma_f32_32x32x16_bf16 v[16:31], v[230:233], v[242:245], v[16:31]
	ds_read_b64_tr_b16 v[238:239], v249 offset:21504
	ds_read_b64_tr_b16 v[240:241], v249 offset:23552
	ds_read_b64_tr_b16 v[242:243], v249 offset:22016
	ds_read_b64_tr_b16 v[244:245], v249 offset:24064
	s_waitcnt lgkmcnt(8)
	v_mfma_f32_32x32x16_bf16 v[32:47], v[234:237], v[136:139], v[32:47]
	v_mfma_f32_32x32x16_bf16 v[16:31], v[234:237], v[140:143], v[16:31]
	s_waitcnt lgkmcnt(0)
	v_mfma_f32_32x32x16_bf16 v[48:63], v[230:233], v[128:131], v[48:63]
	s_waitcnt vmcnt(0)
	s_barrier
	s_add_u32 s86, s86, 0x4000
	s_addc_u32 s87, s87, 0
	s_add_u32 s2, s2, 0x8000
	s_addc_u32 s3, s3, 0
	v_mfma_f32_32x32x16_bf16 v[0:15], v[230:233], v[132:135], v[0:15]
	v_mfma_f32_32x32x16_bf16 v[48:63], v[234:237], v[238:241], v[48:63]
	v_mfma_f32_32x32x16_bf16 v[0:15], v[234:237], v[242:245], v[0:15]
	s_add_i32 s84, s84, 0x8000
	s_cmp_eq_u32 s84, 0x18000
	s_cselect_b32 s84, 0, s84
	s_add_i32 s40, s40, 1
	s_cmpk_eq_i32 s40, 0x82
	s_cbranch_scc0 .LBB0_1023
	s_barrier
	s_branch .Lattn_join_m1

; #define SBAR() __builtin_amdgcn_sched_barrier(0)
; #define PVR(S, DA, DB, vbase) do { S[0] = tr_read<v_rd_off(DA, 0, 0)>(vbase); S[1] = tr_read<v_rd_off(DA, 0, 1)>(vbase); S[2] = tr_read<v_rd_off(DB, 0, 0)>(vbase); S[3] = tr_read<v_rd_off(DB, 0, 1)>(vbase); \
;     S[4] = tr_read<v_rd_off(DA, 1, 0)>(vbase); S[5] = tr_read<v_rd_off(DA, 1, 1)>(vbase); S[6] = tr_read<v_rd_off(DB, 1, 0)>(vbase); S[7] = tr_read<v_rd_off(DB, 1, 1)>(vbase); } while (0)
; #define RAWBAR() do { asm volatile("s_waitcnt lgkmcnt(0)" ::: "memory"); __builtin_amdgcn_s_barrier(); asm volatile("" ::: "memory"); } while (0)
; #define RAWBAR() do { asm volatile("s_waitcnt lgkmcnt(0)" ::: "memory"); __builtin_amdgcn_s_barrier(); asm volatile("" ::: "memory"); } while (0)
; #define RAWBAR() do { asm volatile("s_waitcnt lgkmcnt(0)" ::: "memory"); __builtin_amdgcn_s_barrier(); asm volatile("" ::: "memory"); } while (0)
; #define RAWBAR() do { asm volatile("s_waitcnt lgkmcnt(0)" ::: "memory"); __builtin_amdgcn_s_barrier(); asm volatile("" ::: "memory"); } while (0)
; #define RAWBAR() do { asm volatile("s_waitcnt lgkmcnt(0)" ::: "memory"); __builtin_amdgcn_s_barrier(); asm volatile("" ::: "memory"); } while (0)
; template <int MODE> ...
;     ...
;   for (int j = 0; j < NT; ++j) {
;     const int buf = j & 1;
;     if (j + 1 < NT) { STAGE((j + 1) * KVBLK, buf ^ 1); }
;     const char* Kb = K_lds + buf * 16384;
;     f32x16 pe = {}, po = {};
; #pragma unroll
;     for (int d0 = 0; d0 < 8; d0 += 2) {
;       const bf16x8 k0 = *reinterpret_cast<const bf16x8*>(Kb + KSWZ(krow, (d0 * 16 + hi * 8) * 2));
;       const bf16x8 k1 = *reinterpret_cast<const bf16x8*>(Kb + KSWZ(krow, ((d0 + 1) * 16 + hi * 8) * 2));
;       pe = __builtin_amdgcn_mfma_f32_32x32x16_bf16(k0, qr[d0], pe, 0, 0, 0);
;       po = __builtin_amdgcn_mfma_f32_32x32x16_bf16(k1, qr[d0 + 1], po, 0, 0, 0); }
;     const int vo = vb0 + buf * 32768;
;     s16x4 R0_[8], R1_[8];
;     PVR(R0_, 0, 1, vo);
;     f32x16 p;
; #pragma unroll
;     for (int r = 0; r < 16; ++r) p[r] = __builtin_amdgcn_exp2f(fmaf(pe[r] + po[r], C, negMc));
;     float ps = 0.f;
; #pragma unroll
;     for (int r = 0; r < 16; ++r) ps += p[r];
;     lsum += ps;
;     const bf16x8 own0 = pk8(p, 0), own1 = pk8(p, 8);
;     SBAR();
;     PV_TAIL4(o, vo, vo + 16384, own0, own1);
;     asm volatile("s_waitcnt vmcnt(0)" ::: "memory");
;     RAWBAR();
;   }
.LattnB_m1:
	ds_read_b128 v[230:233], v229 offset:16384
	ds_read_b128 v[234:237], v228 offset:16384
	ds_read_b128 v[238:241], v227 offset:16384
	ds_read_b128 v[242:245], v226 offset:16384
	v_exp_f32_e32 v144, v144
	v_exp_f32_e32 v145, v145
	v_exp_f32_e32 v146, v146
	v_exp_f32_e32 v147, v147
	s_waitcnt lgkmcnt(2)
	v_mfma_f32_32x32x16_bf16 v[128:143], v[230:233], v[188:191], 0
	v_mfma_f32_32x32x16_bf16 v[128:143], v[234:237], v[184:187], v[128:143]
	ds_read_b128 v[230:233], v204 offset:16384
	ds_read_b128 v[234:237], v205 offset:16384
	v_exp_f32_e32 v148, v148
	v_exp_f32_e32 v149, v149
	v_exp_f32_e32 v150, v150
	v_exp_f32_e32 v151, v151
	v_add_f32_e32 v250, v144, v145
	v_add_f32_e32 v250, v146, v250
	v_add_f32_e32 v250, v147, v250
	s_waitcnt lgkmcnt(2)
	v_mfma_f32_32x32x16_bf16 v[128:143], v[238:241], v[180:183], v[128:143]
	v_mfma_f32_32x32x16_bf16 v[128:143], v[242:245], v[176:179], v[128:143]
	ds_read_b128 v[238:241], v206 offset:16384
	ds_read_b128 v[242:245], v207 offset:16384
	v_exp_f32_e32 v152, v152
	v_exp_f32_e32 v153, v153
	v_exp_f32_e32 v154, v154
	v_exp_f32_e32 v155, v155
	v_add_f32_e32 v250, v148, v250
	v_add_f32_e32 v250, v149, v250
	v_add_f32_e32 v250, v150, v250
	v_add_f32_e32 v250, v151, v250
	s_waitcnt lgkmcnt(2)
	v_mfma_f32_32x32x16_bf16 v[128:143], v[230:233], v[172:175], v[128:143]
	v_mfma_f32_32x32x16_bf16 v[128:143], v[234:237], v[168:171], v[128:143]
	v_exp_f32_e32 v156, v156
	v_exp_f32_e32 v157, v157
	v_exp_f32_e32 v158, v158
	v_exp_f32_e32 v159, v159
	v_add_f32_e32 v250, v152, v250
	v_add_f32_e32 v250, v153, v250
	v_add_f32_e32 v250, v154, v250
	v_add_f32_e32 v250, v155, v250
	v_cvt_pk_bf16_f32 v230, v144, v145
	v_cvt_pk_bf16_f32 v231, v146, v147
	v_cvt_pk_bf16_f32 v232, v148, v149
	v_cvt_pk_bf16_f32 v233, v150, v151
	v_add_u32_e32 v249, s84, v218
	ds_read_b64_tr_b16 v[144:145], v249 offset:0
	ds_read_b64_tr_b16 v[146:147], v249 offset:2048
	ds_read_b64_tr_b16 v[148:149], v249 offset:512
	ds_read_b64_tr_b16 v[150:151], v249 offset:2560
	s_waitcnt lgkmcnt(4)
	v_mfma_f32_32x32x16_bf16 v[128:143], v[238:241], v[164:167], v[128:143]
	v_mfma_f32_32x32x16_bf16 v[128:143], v[242:245], v[160:163], v[128:143]
	s_waitcnt vmcnt(0)
	s_barrier
	s_add_u32 s86, s86, 0x4000
	s_addc_u32 s87, s87, 0
	s_add_u32 s2, s2, 0x8000
	s_addc_u32 s3, s3, 0
	s_sub_u32 s85, s84, 0x8000
	s_cmp_eq_u32 s84, 0
	s_cselect_b32 s85, 0x10000, s85
	ds_read_b64_tr_b16 v[238:239], v249 offset:4096
	ds_read_b64_tr_b16 v[240:241], v249 offset:6144
	ds_read_b64_tr_b16 v[242:243], v249 offset:4608
	ds_read_b64_tr_b16 v[244:245], v249 offset:6656
	v_add_f32_e32 v250, v156, v250
	v_add_f32_e32 v250, v157, v250
	v_add_f32_e32 v250, v158, v250
	v_add_f32_e32 v250, v159, v250
	v_cvt_pk_bf16_f32 v234, v152, v153
	v_cvt_pk_bf16_f32 v235, v154, v155
	v_cvt_pk_bf16_f32 v236, v156, v157
	v_cvt_pk_bf16_f32 v237, v158, v159
	v_add_f32_e32 v219, v219, v250
	ds_read_b64_tr_b16 v[152:153], v249 offset:1024
	ds_read_b64_tr_b16 v[154:155], v249 offset:3072
	ds_read_b64_tr_b16 v[156:157], v249 offset:1536
	ds_read_b64_tr_b16 v[158:159], v249 offset:3584
	s_waitcnt lgkmcnt(8)
	v_mfma_f32_32x32x16_bf16 v[112:127], v[230:233], v[144:147], v[112:127]
	v_mfma_f32_32x32x16_bf16 v[96:111], v[230:233], v[148:151], v[96:111]
	ds_read_b64_tr_b16 v[144:145], v249 offset:5120
	ds_read_b64_tr_b16 v[146:147], v249 offset:7168
	ds_read_b64_tr_b16 v[148:149], v249 offset:5632
	ds_read_b64_tr_b16 v[150:151], v249 offset:7680
	s_add_i32 s30, s85, s34
	s_add_i32 m0, s30, 0x8000
	s_nop 0
	global_load_lds_dwordx4 v222, s[2:3] sc1
	s_waitcnt lgkmcnt(8)
	v_mfma_f32_32x32x16_bf16 v[112:127], v[234:237], v[238:241], v[112:127]
	v_mfma_f32_32x32x16_bf16 v[96:111], v[234:237], v[242:245], v[96:111]
	ds_read_b64_tr_b16 v[238:239], v249 offset:16384
	ds_read_b64_tr_b16 v[240:241], v249 offset:18432
	ds_read_b64_tr_b16 v[242:243], v249 offset:16896
	ds_read_b64_tr_b16 v[244:245], v249 offset:18944
	s_add_i32 s30, s85, s34
	s_add_i32 m0, s30, 0xa000
	s_nop 0
	global_load_lds_dwordx4 v221, s[2:3] sc1
	s_waitcnt lgkmcnt(8)
	v_mfma_f32_32x32x16_bf16 v[80:95], v[230:233], v[152:155], v[80:95]
	v_mfma_f32_32x32x16_bf16 v[64:79], v[230:233], v[156:159], v[64:79]
	ds_read_b64_tr_b16 v[152:153], v249 offset:20480
	ds_read_b64_tr_b16 v[154:155], v249 offset:22528
	ds_read_b64_tr_b16 v[156:157], v249 offset:20992
	ds_read_b64_tr_b16 v[158:159], v249 offset:23040
	s_add_i32 s30, s85, s34
	s_add_i32 m0, s30, 0xc000
	s_nop 0
	global_load_lds_dwordx4 v246, s[2:3] sc1
	s_waitcnt lgkmcnt(8)
	v_mfma_f32_32x32x16_bf16 v[80:95], v[234:237], v[144:147], v[80:95]
	v_mfma_f32_32x32x16_bf16 v[64:79], v[234:237], v[148:151], v[64:79]
	ds_read_b64_tr_b16 v[144:145], v249 offset:17408
	ds_read_b64_tr_b16 v[146:147], v249 offset:19456
	ds_read_b64_tr_b16 v[148:149], v249 offset:17920
	ds_read_b64_tr_b16 v[150:151], v249 offset:19968
	s_add_i32 s30, s85, s34
	s_add_i32 m0, s30, 0xe000
	s_nop 0
	global_load_lds_dwordx4 v247, s[2:3] sc1
	s_waitcnt lgkmcnt(8)
	v_mfma_f32_32x32x16_bf16 v[32:47], v[230:233], v[238:241], v[32:47]
	v_mfma_f32_32x32x16_bf16 v[16:31], v[230:233], v[242:245], v[16:31]
	ds_read_b64_tr_b16 v[238:239], v249 offset:21504
	ds_read_b64_tr_b16 v[240:241], v249 offset:23552
	ds_read_b64_tr_b16 v[242:243], v249 offset:22016
	ds_read_b64_tr_b16 v[244:245], v249 offset:24064
	s_add_i32 m0, s34, 0x4000
	s_nop 0
	global_load_lds_dwordx4 v225, s[86:87] sc1
	s_waitcnt lgkmcnt(8)
	v_mfma_f32_32x32x16_bf16 v[32:47], v[234:237], v[152:155], v[32:47]
	v_mfma_f32_32x32x16_bf16 v[16:31], v[234:237], v[156:159], v[16:31]
	s_add_i32 m0, s34, 0x6000
	s_nop 0
	global_load_lds_dwordx4 v223, s[86:87] sc1
	s_waitcnt lgkmcnt(0)
; #define SBAR() __builtin_amdgcn_sched_barrier(0)
; #define PVR(S, DA, DB, vbase) do { S[0] = tr_read<v_rd_off(DA, 0, 0)>(vbase); S[1] = tr_read<v_rd_off(DA, 0, 1)>(vbase); S[2] = tr_read<v_rd_off(DB, 0, 0)>(vbase); S[3] = tr_read<v_rd_off(DB, 0, 1)>(vbase); \
;     S[4] = tr_read<v_rd_off(DA, 1, 0)>(vbase); S[5] = tr_read<v_rd_off(DA, 1, 1)>(vbase); S[6] = tr_read<v_rd_off(DB, 1, 0)>(vbase); S[7] = tr_read<v_rd_off(DB, 1, 1)>(vbase); } while (0)
; #define RAWBAR() do { asm volatile("s_waitcnt lgkmcnt(0)" ::: "memory"); __builtin_amdgcn_s_barrier(); asm volatile("" ::: "memory"); } while (0)
; #define RAWBAR() do { asm volatile("s_waitcnt lgkmcnt(0)" ::: "memory"); __builtin_amdgcn_s_barrier(); asm volatile("" ::: "memory"); } while (0)
; #define RAWBAR() do { asm volatile("s_waitcnt lgkmcnt(0)" ::: "memory"); __builtin_amdgcn_s_barrier(); asm volatile("" ::: "memory"); } while (0)
; #define RAWBAR() do { asm volatile("s_waitcnt lgkmcnt(0)" ::: "memory"); __builtin_amdgcn_s_barrier(); asm volatile("" ::: "memory"); } while (0)
; #define RAWBAR() do { asm volatile("s_waitcnt lgkmcnt(0)" ::: "memory"); __builtin_amdgcn_s_barrier(); asm volatile("" ::: "memory"); } while (0)
; template <int MODE> ...
;     ...
;   for (int j = 0; j < NT; ++j) {
;     const int buf = j & 1;
;     if (j + 1 < NT) { STAGE((j + 1) * KVBLK, buf ^ 1); }
;     const char* Kb = K_lds + buf * 16384;
;     f32x16 pe = {}, po = {};
; #pragma unroll
;     for (int d0 = 0; d0 < 8; d0 += 2) {
;       const bf16x8 k0 = *reinterpret_cast<const bf16x8*>(Kb + KSWZ(krow, (d0 * 16 + hi * 8) * 2));
;       const bf16x8 k1 = *reinterpret_cast<const bf16x8*>(Kb + KSWZ(krow, ((d0 + 1) * 16 + hi * 8) * 2));
;       pe = __builtin_amdgcn_mfma_f32_32x32x16_bf16(k0, qr[d0], pe, 0, 0, 0);
;       po = __builtin_amdgcn_mfma_f32_32x32x16_bf16(k1, qr[d0 + 1], po, 0, 0, 0); }
;     const int vo = vb0 + buf * 32768;
;     s16x4 R0_[8], R1_[8];
;     PVR(R0_, 0, 1, vo);
;     f32x16 p;
; #pragma unroll
;     for (int r = 0; r < 16; ++r) p[r] = __builtin_amdgcn_exp2f(fmaf(pe[r] + po[r], C, negMc));
;     float ps = 0.f;
; #pragma unroll
;     for (int r = 0; r < 16; ++r) ps += p[r];
;     lsum += ps;
;     const bf16x8 own0 = pk8(p, 0), own1 = pk8(p, 8);
;     SBAR();
;     PV_TAIL4(o, vo, vo + 16384, own0, own1);
;     asm volatile("s_waitcnt vmcnt(0)" ::: "memory");
;     RAWBAR();
;   }
	v_mfma_f32_32x32x16_bf16 v[48:63], v[230:233], v[144:147], v[48:63]
	v_mfma_f32_32x32x16_bf16 v[0:15], v[230:233], v[148:151], v[0:15]
	v_mfma_f32_32x32x16_bf16 v[48:63], v[234:237], v[238:241], v[48:63]
	v_mfma_f32_32x32x16_bf16 v[0:15], v[234:237], v[242:245], v[0:15]
	s_add_i32 s84, s84, 0x8000
	s_cmp_eq_u32 s84, 0x18000
	s_cselect_b32 s84, 0, s84
	ds_read_b128 v[230:233], v229 offset:0
	ds_read_b128 v[234:237], v228 offset:0
	ds_read_b128 v[238:241], v227 offset:0
	ds_read_b128 v[242:245], v226 offset:0
	v_exp_f32_e32 v128, v128
	v_exp_f32_e32 v129, v129
	v_exp_f32_e32 v130, v130
	v_exp_f32_e32 v131, v131
	s_waitcnt lgkmcnt(2)
	v_mfma_f32_32x32x16_bf16 v[144:159], v[230:233], v[188:191], 0
	v_mfma_f32_32x32x16_bf16 v[144:159], v[234:237], v[184:187], v[144:159]
	ds_read_b128 v[230:233], v204 offset:0
	ds_read_b128 v[234:237], v205 offset:0
	v_exp_f32_e32 v132, v132
	v_exp_f32_e32 v133, v133
	v_exp_f32_e32 v134, v134
	v_exp_f32_e32 v135, v135
	v_add_f32_e32 v250, v128, v129
	v_add_f32_e32 v250, v130, v250
	v_add_f32_e32 v250, v131, v250
	s_waitcnt lgkmcnt(2)
	v_mfma_f32_32x32x16_bf16 v[144:159], v[238:241], v[180:183], v[144:159]
	v_mfma_f32_32x32x16_bf16 v[144:159], v[242:245], v[176:179], v[144:159]
	ds_read_b128 v[238:241], v206 offset:0
	ds_read_b128 v[242:245], v207 offset:0
	v_exp_f32_e32 v136, v136
	v_exp_f32_e32 v137, v137
	v_exp_f32_e32 v138, v138
	v_exp_f32_e32 v139, v139
	v_add_f32_e32 v250, v132, v250
	v_add_f32_e32 v250, v133, v250
	v_add_f32_e32 v250, v134, v250
	v_add_f32_e32 v250, v135, v250
	s_waitcnt lgkmcnt(2)
	v_mfma_f32_32x32x16_bf16 v[144:159], v[230:233], v[172:175], v[144:159]
	v_mfma_f32_32x32x16_bf16 v[144:159], v[234:237], v[168:171], v[144:159]
	v_exp_f32_e32 v140, v140
	v_exp_f32_e32 v141, v141
	v_exp_f32_e32 v142, v142
	v_exp_f32_e32 v143, v143
	v_add_f32_e32 v250, v136, v250
	v_add_f32_e32 v250, v137, v250
	v_add_f32_e32 v250, v138, v250
	v_add_f32_e32 v250, v139, v250
	v_cvt_pk_bf16_f32 v230, v128, v129
	v_cvt_pk_bf16_f32 v231, v130, v131
	v_cvt_pk_bf16_f32 v232, v132, v133
	v_cvt_pk_bf16_f32 v233, v134, v135
	v_add_u32_e32 v249, s84, v218
	ds_read_b64_tr_b16 v[128:129], v249 offset:0
	ds_read_b64_tr_b16 v[130:131], v249 offset:2048
	ds_read_b64_tr_b16 v[132:133], v249 offset:512
	ds_read_b64_tr_b16 v[134:135], v249 offset:2560
	s_waitcnt lgkmcnt(4)
	v_mfma_f32_32x32x16_bf16 v[144:159], v[238:241], v[164:167], v[144:159]
	v_mfma_f32_32x32x16_bf16 v[144:159], v[242:245], v[160:163], v[144:159]
	s_waitcnt vmcnt(0)
	s_barrier
	s_add_u32 s86, s86, 0x4000
	s_addc_u32 s87, s87, 0
	s_add_u32 s2, s2, 0x8000
	s_addc_u32 s3, s3, 0
	s_sub_u32 s85, s84, 0x8000
	s_cmp_eq_u32 s84, 0
	s_cselect_b32 s85, 0x10000, s85
	ds_read_b64_tr_b16 v[238:239], v249 offset:4096
	ds_read_b64_tr_b16 v[240:241], v249 offset:6144
	ds_read_b64_tr_b16 v[242:243], v249 offset:4608
	ds_read_b64_tr_b16 v[244:245], v249 offset:6656
	v_add_f32_e32 v250, v140, v250
	v_add_f32_e32 v250, v141, v250
	v_add_f32_e32 v250, v142, v250
	v_add_f32_e32 v250, v143, v250
	v_cvt_pk_bf16_f32 v234, v136, v137
	v_cvt_pk_bf16_f32 v235, v138, v139
	v_cvt_pk_bf16_f32 v236, v140, v141
	v_cvt_pk_bf16_f32 v237, v142, v143
	v_add_f32_e32 v219, v219, v250
	ds_read_b64_tr_b16 v[136:137], v249 offset:1024
	ds_read_b64_tr_b16 v[138:139], v249 offset:3072
	ds_read_b64_tr_b16 v[140:141], v249 offset:1536
	ds_read_b64_tr_b16 v[142:143], v249 offset:3584
	s_waitcnt lgkmcnt(8)
	v_mfma_f32_32x32x16_bf16 v[112:127], v[230:233], v[128:131], v[112:127]
	v_mfma_f32_32x32x16_bf16 v[96:111], v[230:233], v[132:135], v[96:111]
	ds_read_b64_tr_b16 v[128:129], v249 offset:5120
	ds_read_b64_tr_b16 v[130:131], v249 offset:7168
	ds_read_b64_tr_b16 v[132:133], v249 offset:5632
	ds_read_b64_tr_b16 v[134:135], v249 offset:7680
	s_add_i32 s30, s85, s34
	s_add_i32 m0, s30, 0x8000
	s_nop 0
	global_load_lds_dwordx4 v222, s[2:3] sc1
	s_waitcnt lgkmcnt(8)
	v_mfma_f32_32x32x16_bf16 v[112:127], v[234:237], v[238:241], v[112:127]
	v_mfma_f32_32x32x16_bf16 v[96:111], v[234:237], v[242:245], v[96:111]
	ds_read_b64_tr_b16 v[238:239], v249 offset:16384
	ds_read_b64_tr_b16 v[240:241], v249 offset:18432
	ds_read_b64_tr_b16 v[242:243], v249 offset:16896
	ds_read_b64_tr_b16 v[244:245], v249 offset:18944
	s_add_i32 s30, s85, s34
	s_add_i32 m0, s30, 0xa000
	s_nop 0
	global_load_lds_dwordx4 v221, s[2:3] sc1
	s_waitcnt lgkmcnt(8)
	v_mfma_f32_32x32x16_bf16 v[80:95], v[230:233], v[136:139], v[80:95]
	v_mfma_f32_32x32x16_bf16 v[64:79], v[230:233], v[140:143], v[64:79]
	ds_read_b64_tr_b16 v[136:137], v249 offset:20480
	ds_read_b64_tr_b16 v[138:139], v249 offset:22528
	ds_read_b64_tr_b16 v[140:141], v249 offset:20992
	ds_read_b64_tr_b16 v[142:143], v249 offset:23040
	s_add_i32 s30, s85, s34
	s_add_i32 m0, s30, 0xc000
	s_nop 0
	global_load_lds_dwordx4 v246, s[2:3] sc1
	s_waitcnt lgkmcnt(8)
	v_mfma_f32_32x32x16_bf16 v[80:95], v[234:237], v[128:131], v[80:95]
	v_mfma_f32_32x32x16_bf16 v[64:79], v[234:237], v[132:135], v[64:79]
	ds_read_b64_tr_b16 v[128:129], v249 offset:17408
	ds_read_b64_tr_b16 v[130:131], v249 offset:19456
	ds_read_b64_tr_b16 v[132:133], v249 offset:17920
	ds_read_b64_tr_b16 v[134:135], v249 offset:19968
	s_add_i32 s30, s85, s34
	s_add_i32 m0, s30, 0xe000
	s_nop 0
	global_load_lds_dwordx4 v247, s[2:3] sc1
	s_waitcnt lgkmcnt(8)
	v_mfma_f32_32x32x16_bf16 v[32:47], v[230:233], v[238:241], v[32:47]
	v_mfma_f32_32x32x16_bf16 v[16:31], v[230:233], v[242:245], v[16:31]
	ds_read_b64_tr_b16 v[238:239], v249 offset:21504
	ds_read_b64_tr_b16 v[240:241], v249 offset:23552
	ds_read_b64_tr_b16 v[242:243], v249 offset:22016
	ds_read_b64_tr_b16 v[244:245], v249 offset:24064
	s_mov_b32 m0, s34
	s_nop 0
	global_load_lds_dwordx4 v225, s[86:87] sc1
	s_waitcnt lgkmcnt(8)
	v_mfma_f32_32x32x16_bf16 v[32:47], v[234:237], v[136:139], v[32:47]
	v_mfma_f32_32x32x16_bf16 v[16:31], v[234:237], v[140:143], v[16:31]
	s_add_i32 m0, s34, 0x2000
	s_nop 0
	global_load_lds_dwordx4 v223, s[86:87] sc1
	s_waitcnt lgkmcnt(0)
	v_mfma_f32_32x32x16_bf16 v[48:63], v[230:233], v[128:131], v[48:63]
	v_mfma_f32_32x32x16_bf16 v[0:15], v[230:233], v[132:135], v[0:15]
	v_mfma_f32_32x32x16_bf16 v[48:63], v[234:237], v[238:241], v[48:63]
	v_mfma_f32_32x32x16_bf16 v[0:15], v[234:237], v[242:245], v[0:15]
	s_add_i32 s84, s84, 0x8000
	s_cmp_eq_u32 s84, 0x18000
	s_cselect_b32 s84, 0, s84
	s_add_i32 s40, s40, 1
	s_cmpk_eq_i32 s40, 0x82
	s_cbranch_scc0 .LattnB_m1
	s_waitcnt vmcnt(0)
	s_barrier
